# hoist 8 serialized gate loads in phase-F merge epilogue; batch the x/gate loads of the residual epilogues (G,J) 8-deep with counted vmcnt
# speedup vs baseline: 1.0174x; 1.0174x over previous
; __device__ __forceinline__ float sigmoidf_(float x) { return __builtin_amdgcn_rcpf(1.f + __builtin_amdgcn_exp2f(-1.44269504f * x)); }
;     __device__ __forceinline__ void operator()(f32x4 (&acc)[2][2][4][2], const Unit& u, int wr, int wc, int fr, int fq) const {
;         const int mode = u.batch; const int goff = mode == 0 ? 1024 : (mode == 1 ? 0 : 2048);
; #pragma unroll
;         for (int ai = 0; ai < 2; ++ai)
; #pragma unroll
;             for (int m = 0; m < 4; ++m) {
;                 const size_t r = (size_t)(u.pm * 256 + ai * 128 + wr * 64 + m * 16 + fr); const int c = u.pn * 128 + wc * 32 + 8 * fq;
;                 const u32x4 gq = *(const u32x4*)(GT + r * 3072 + goff + c);
;                 float gf[8]; unpack8(gq, gf);
;                 const f32x4 g0 = {gf[0], gf[1], gf[2], gf[3]}, g1 = {gf[4], gf[5], gf[6], gf[7]};
;                 const f32x4 v0 = acc[ai][1][m][0], v1 = acc[ai][1][m][1]; f32x4 M0 = acc[ai][0][m][0], M1 = acc[ai][0][m][1];
;                 if (mode == 0) {
; #pragma unroll
;                     for (int i = 0; i < 4; ++i) { M0[i] = g0[i] * sigmoidf_(M0[i]) * v0[i]; M1[i] = g1[i] * sigmoidf_(M1[i]) * v1[i]; }
;                 } else { M0 += g0 * v0; M1 += g1 * v1; }
.LBB0_844:
	s_cmp_eq_u32 s45, 1
	s_cselect_b32 s5, 0, 0x800
	s_cmp_lg_u32 s45, 0
	s_cselect_b64 s[0:1], -1, 0
	s_and_b64 vcc, s[0:1], exec
	s_cselect_b32 s6, s5, 0x400
	s_lshl_b32 s4, s4, 8
	v_mov_b32_e32 v130, v229
	v_mov_b32_e32 v131, v230
	s_add_i32 s4, s4, s92
	v_mov_b64_e32 v[132:133], s[58:59]
	v_add_u32_e32 v140, s4, v130
	s_lshl_b32 s4, s44, 7
	s_or_b32 s4, s4, s93
	v_lshl_add_u32 v130, v131, 3, s4
	v_mad_i64_i32 v[132:133], s[4:5], v140, s97, v[132:133]
	s_lshl_b32 s6, s6, 1
	v_lshl_add_u64 v[132:133], v[132:133], 0, s[6:7]
	v_ashrrev_i32_e32 v131, 31, v130
	v_lshl_add_u64 v[132:133], v[130:131], 1, v[132:133]
	s_mov_b32 s100, 0x18000
	s_mov_b32 s101, 0
	v_lshl_add_u64 v[150:151], v[132:133], 0, s[100:101]
	global_load_dwordx4 v[132:135], v[132:133], off
	global_load_dwordx4 v[156:159], v[150:151], off
	v_lshl_add_u64 v[150:151], v[150:151], 0, s[100:101]
	global_load_dwordx4 v[160:163], v[150:151], off
	v_lshl_add_u64 v[150:151], v[150:151], 0, s[100:101]
	global_load_dwordx4 v[164:167], v[150:151], off
	s_mov_b32 s100, 0x78000
	v_lshl_add_u64 v[150:151], v[150:151], 0, s[100:101]
	global_load_dwordx4 v[168:171], v[150:151], off
	s_mov_b32 s100, 0x18000
	v_lshl_add_u64 v[150:151], v[150:151], 0, s[100:101]
	global_load_dwordx4 v[172:175], v[150:151], off
	v_lshl_add_u64 v[150:151], v[150:151], 0, s[100:101]
	global_load_dwordx4 v[176:179], v[150:151], off
	v_lshl_add_u64 v[150:151], v[150:151], 0, s[100:101]
	global_load_dwordx4 v[180:183], v[150:151], off
	s_mov_b64 s[4:5], -1
	s_waitcnt vmcnt(7)
	v_lshlrev_b32_e32 v148, 16, v132
	v_and_b32_e32 v149, 0xffff0000, v132
	v_lshlrev_b32_e32 v144, 16, v133
	v_and_b32_e32 v145, 0xffff0000, v133
	v_lshlrev_b32_e32 v146, 16, v134
	v_and_b32_e32 v147, 0xffff0000, v134
	v_lshlrev_b32_e32 v142, 16, v135
	v_and_b32_e32 v143, 0xffff0000, v135
	s_cbranch_vccz .LBB0_846
	v_pk_fma_f32 v[136:137], v[128:129], v[144:145], v[96:97]
	v_pk_fma_f32 v[132:133], v[126:127], v[148:149], v[94:95]
	v_pk_fma_f32 v[138:139], v[124:125], v[142:143], v[92:93]
	v_pk_fma_f32 v[134:135], v[122:123], v[146:147], v[90:91]
	s_mov_b64 s[4:5], 0

; __device__ __forceinline__ float sigmoidf_(float x) { return __builtin_amdgcn_rcpf(1.f + __builtin_amdgcn_exp2f(-1.44269504f * x)); }
;     __device__ __forceinline__ void operator()(f32x4 (&acc)[2][2][4][2], const Unit& u, int wr, int wc, int fr, int fq) const {
;     ...
;                 const size_t r = (size_t)(u.pm * 256 + ai * 128 + wr * 64 + m * 16 + fr); const int c = u.pn * 128 + wc * 32 + 8 * fq;
;                 const u32x4 gq = *(const u32x4*)(GT + r * 3072 + goff + c);
;                 float gf[8]; unpack8(gq, gf);
;                 const f32x4 g0 = {gf[0], gf[1], gf[2], gf[3]}, g1 = {gf[4], gf[5], gf[6], gf[7]};
;                 const f32x4 v0 = acc[ai][1][m][0], v1 = acc[ai][1][m][1]; f32x4 M0 = acc[ai][0][m][0], M1 = acc[ai][0][m][1];
;                 if (mode == 0) {
; #pragma unroll
;                     for (int i = 0; i < 4; ++i) { M0[i] = g0[i] * sigmoidf_(M0[i]) * v0[i]; M1[i] = g1[i] * sigmoidf_(M1[i]) * v1[i]; }
;                 } else { M0 += g0 * v0; M1 += g1 * v1; }
.LBB0_850:
	s_nop 1
	v_add_u32_e32 v90, 16, v140
	v_mov_b64_e32 v[92:93], s[58:59]
	v_mad_i64_i32 v[92:93], s[24:25], v90, s97, v[92:93]
	v_lshl_add_u64 v[92:93], v[92:93], 0, s[6:7]
	v_lshl_add_u64 v[92:93], v[130:131], 1, v[92:93]
	v_cndmask_b32_e64 v91, 0, 1, s[0:1]
	v_cmp_ne_u32_e64 s[42:43], 1, v91
	s_andn2_b64 vcc, exec, s[0:1]
	s_mov_b64 s[0:1], -1
	s_waitcnt vmcnt(6)
	v_lshlrev_b32_e32 v142, 16, v156
	v_and_b32_e32 v143, 0xffff0000, v156
	v_lshlrev_b32_e32 v94, 16, v157
	v_and_b32_e32 v95, 0xffff0000, v157
	v_lshlrev_b32_e32 v96, 16, v158
	v_and_b32_e32 v97, 0xffff0000, v158
	v_lshlrev_b32_e32 v92, 16, v159
	v_and_b32_e32 v93, 0xffff0000, v159
	s_cbranch_vccnz .LBB0_881
	v_pk_fma_f32 v[126:127], v[120:121], v[94:95], v[80:81]
	v_pk_fma_f32 v[122:123], v[118:119], v[142:143], v[78:79]
	v_pk_fma_f32 v[128:129], v[116:117], v[92:93], v[76:77]
	v_pk_fma_f32 v[124:125], v[114:115], v[96:97], v[74:75]
	s_cbranch_execz .LBB0_882

; __device__ __forceinline__ float sigmoidf_(float x) { return __builtin_amdgcn_rcpf(1.f + __builtin_amdgcn_exp2f(-1.44269504f * x)); }
;     __device__ __forceinline__ void operator()(f32x4 (&acc)[2][2][4][2], const Unit& u, int wr, int wc, int fr, int fq) const {
;     ...
;                 const size_t r = (size_t)(u.pm * 256 + ai * 128 + wr * 64 + m * 16 + fr); const int c = u.pn * 128 + wc * 32 + 8 * fq;
;                 const u32x4 gq = *(const u32x4*)(GT + r * 3072 + goff + c);
;                 float gf[8]; unpack8(gq, gf);
;                 const f32x4 g0 = {gf[0], gf[1], gf[2], gf[3]}, g1 = {gf[4], gf[5], gf[6], gf[7]};
;                 const f32x4 v0 = acc[ai][1][m][0], v1 = acc[ai][1][m][1]; f32x4 M0 = acc[ai][0][m][0], M1 = acc[ai][0][m][1];
;                 if (mode == 0) {
; #pragma unroll
;                     for (int i = 0; i < 4; ++i) { M0[i] = g0[i] * sigmoidf_(M0[i]) * v0[i]; M1[i] = g1[i] * sigmoidf_(M1[i]) * v1[i]; }
;                 } else { M0 += g0 * v0; M1 += g1 * v1; }
.LBB0_854:
	s_nop 1
	v_add_u32_e32 v74, 32, v140
	v_mov_b64_e32 v[76:77], s[58:59]
	v_mad_i64_i32 v[76:77], s[0:1], v74, s97, v[76:77]
	v_lshl_add_u64 v[76:77], v[76:77], 0, s[6:7]
	v_lshl_add_u64 v[76:77], v[130:131], 1, v[76:77]
	s_and_b64 vcc, exec, s[42:43]
	s_mov_b64 s[0:1], -1
	s_waitcnt vmcnt(5)
	v_lshlrev_b32_e32 v90, 16, v160
	v_and_b32_e32 v91, 0xffff0000, v160
	v_lshlrev_b32_e32 v78, 16, v161
	v_and_b32_e32 v79, 0xffff0000, v161
	v_lshlrev_b32_e32 v80, 16, v162
	v_and_b32_e32 v81, 0xffff0000, v162
	v_lshlrev_b32_e32 v76, 16, v163
	v_and_b32_e32 v77, 0xffff0000, v163
	s_cbranch_vccnz .LBB0_883
	v_pk_fma_f32 v[118:119], v[112:113], v[78:79], v[64:65]
	v_pk_fma_f32 v[114:115], v[110:111], v[90:91], v[62:63]
	v_pk_fma_f32 v[120:121], v[108:109], v[76:77], v[60:61]
	v_pk_fma_f32 v[116:117], v[106:107], v[80:81], v[58:59]
	s_cbranch_execz .LBB0_884

; __device__ __forceinline__ float sigmoidf_(float x) { return __builtin_amdgcn_rcpf(1.f + __builtin_amdgcn_exp2f(-1.44269504f * x)); }
;     __device__ __forceinline__ void operator()(f32x4 (&acc)[2][2][4][2], const Unit& u, int wr, int wc, int fr, int fq) const {
;     ...
;                 const size_t r = (size_t)(u.pm * 256 + ai * 128 + wr * 64 + m * 16 + fr); const int c = u.pn * 128 + wc * 32 + 8 * fq;
;                 const u32x4 gq = *(const u32x4*)(GT + r * 3072 + goff + c);
;                 float gf[8]; unpack8(gq, gf);
;                 const f32x4 g0 = {gf[0], gf[1], gf[2], gf[3]}, g1 = {gf[4], gf[5], gf[6], gf[7]};
;                 const f32x4 v0 = acc[ai][1][m][0], v1 = acc[ai][1][m][1]; f32x4 M0 = acc[ai][0][m][0], M1 = acc[ai][0][m][1];
;                 if (mode == 0) {
; #pragma unroll
;                     for (int i = 0; i < 4; ++i) { M0[i] = g0[i] * sigmoidf_(M0[i]) * v0[i]; M1[i] = g1[i] * sigmoidf_(M1[i]) * v1[i]; }
;                 } else { M0 += g0 * v0; M1 += g1 * v1; }
.LBB0_858:
	s_nop 1
	v_add_u32_e32 v58, 48, v140
	v_mov_b64_e32 v[60:61], s[58:59]
	v_mad_i64_i32 v[60:61], s[0:1], v58, s97, v[60:61]
	v_lshl_add_u64 v[60:61], v[60:61], 0, s[6:7]
	v_lshl_add_u64 v[60:61], v[130:131], 1, v[60:61]
	s_and_b64 vcc, exec, s[42:43]
	s_mov_b64 s[0:1], -1
	s_waitcnt vmcnt(4)
	v_lshlrev_b32_e32 v74, 16, v164
	v_and_b32_e32 v75, 0xffff0000, v164
	v_lshlrev_b32_e32 v62, 16, v165
	v_and_b32_e32 v63, 0xffff0000, v165
	v_lshlrev_b32_e32 v64, 16, v166
	v_and_b32_e32 v65, 0xffff0000, v166
	v_lshlrev_b32_e32 v60, 16, v167
	v_and_b32_e32 v61, 0xffff0000, v167
	s_cbranch_vccnz .LBB0_885
	v_pk_fma_f32 v[110:111], v[104:105], v[62:63], v[48:49]
	v_pk_fma_f32 v[106:107], v[102:103], v[74:75], v[46:47]
	v_pk_fma_f32 v[112:113], v[100:101], v[60:61], v[44:45]
	v_pk_fma_f32 v[108:109], v[98:99], v[64:65], v[42:43]
	s_cbranch_execz .LBB0_886

; __device__ __forceinline__ float sigmoidf_(float x) { return __builtin_amdgcn_rcpf(1.f + __builtin_amdgcn_exp2f(-1.44269504f * x)); }
;     __device__ __forceinline__ void operator()(f32x4 (&acc)[2][2][4][2], const Unit& u, int wr, int wc, int fr, int fq) const {
;     ...
;                 const size_t r = (size_t)(u.pm * 256 + ai * 128 + wr * 64 + m * 16 + fr); const int c = u.pn * 128 + wc * 32 + 8 * fq;
;                 const u32x4 gq = *(const u32x4*)(GT + r * 3072 + goff + c);
;                 float gf[8]; unpack8(gq, gf);
;                 const f32x4 g0 = {gf[0], gf[1], gf[2], gf[3]}, g1 = {gf[4], gf[5], gf[6], gf[7]};
;                 const f32x4 v0 = acc[ai][1][m][0], v1 = acc[ai][1][m][1]; f32x4 M0 = acc[ai][0][m][0], M1 = acc[ai][0][m][1];
;                 if (mode == 0) {
; #pragma unroll
;                     for (int i = 0; i < 4; ++i) { M0[i] = g0[i] * sigmoidf_(M0[i]) * v0[i]; M1[i] = g1[i] * sigmoidf_(M1[i]) * v1[i]; }
;                 } else { M0 += g0 * v0; M1 += g1 * v1; }
.LBB0_862:
	s_nop 1
	v_add_u32_e32 v42, 0x80, v140
	v_mov_b64_e32 v[44:45], s[58:59]
	v_mad_i64_i32 v[44:45], s[0:1], v42, s97, v[44:45]
	v_lshl_add_u64 v[44:45], v[44:45], 0, s[6:7]
	v_lshl_add_u64 v[44:45], v[130:131], 1, v[44:45]
	s_and_b64 vcc, exec, s[42:43]
	s_mov_b64 s[0:1], -1
	s_waitcnt vmcnt(3)
	v_lshlrev_b32_e32 v58, 16, v168
	v_and_b32_e32 v59, 0xffff0000, v168
	v_lshlrev_b32_e32 v46, 16, v169
	v_and_b32_e32 v47, 0xffff0000, v169
	v_lshlrev_b32_e32 v48, 16, v170
	v_and_b32_e32 v49, 0xffff0000, v170
	v_lshlrev_b32_e32 v44, 16, v171
	v_and_b32_e32 v45, 0xffff0000, v171
	s_cbranch_vccnz .LBB0_887
	v_pk_fma_f32 v[102:103], v[88:89], v[46:47], v[36:37]
	v_pk_fma_f32 v[98:99], v[86:87], v[58:59], v[34:35]
	v_pk_fma_f32 v[104:105], v[84:85], v[44:45], v[32:33]
	v_pk_fma_f32 v[100:101], v[82:83], v[48:49], v[30:31]
	s_cbranch_execz .LBB0_888

; __device__ __forceinline__ float sigmoidf_(float x) { return __builtin_amdgcn_rcpf(1.f + __builtin_amdgcn_exp2f(-1.44269504f * x)); }
;     __device__ __forceinline__ void operator()(f32x4 (&acc)[2][2][4][2], const Unit& u, int wr, int wc, int fr, int fq) const {
;     ...
;                 const size_t r = (size_t)(u.pm * 256 + ai * 128 + wr * 64 + m * 16 + fr); const int c = u.pn * 128 + wc * 32 + 8 * fq;
;                 const u32x4 gq = *(const u32x4*)(GT + r * 3072 + goff + c);
;                 float gf[8]; unpack8(gq, gf);
;                 const f32x4 g0 = {gf[0], gf[1], gf[2], gf[3]}, g1 = {gf[4], gf[5], gf[6], gf[7]};
;                 const f32x4 v0 = acc[ai][1][m][0], v1 = acc[ai][1][m][1]; f32x4 M0 = acc[ai][0][m][0], M1 = acc[ai][0][m][1];
;                 if (mode == 0) {
; #pragma unroll
;                     for (int i = 0; i < 4; ++i) { M0[i] = g0[i] * sigmoidf_(M0[i]) * v0[i]; M1[i] = g1[i] * sigmoidf_(M1[i]) * v1[i]; }
;                 } else { M0 += g0 * v0; M1 += g1 * v1; }
.LBB0_866:
	s_nop 1
	v_add_u32_e32 v30, 0x90, v140
	v_mov_b64_e32 v[32:33], s[58:59]
	v_mad_i64_i32 v[32:33], s[0:1], v30, s97, v[32:33]
	v_lshl_add_u64 v[32:33], v[32:33], 0, s[6:7]
	v_lshl_add_u64 v[32:33], v[130:131], 1, v[32:33]
	s_and_b64 vcc, exec, s[42:43]
	s_mov_b64 s[0:1], -1
	s_waitcnt vmcnt(2)
	v_lshlrev_b32_e32 v42, 16, v172
	v_and_b32_e32 v43, 0xffff0000, v172
	v_lshlrev_b32_e32 v34, 16, v173
	v_and_b32_e32 v35, 0xffff0000, v173
	v_lshlrev_b32_e32 v36, 16, v174
	v_and_b32_e32 v37, 0xffff0000, v174
	v_lshlrev_b32_e32 v32, 16, v175
	v_and_b32_e32 v33, 0xffff0000, v175
	s_cbranch_vccnz .LBB0_889
	v_pk_fma_f32 v[86:87], v[72:73], v[34:35], v[24:25]
	v_pk_fma_f32 v[82:83], v[70:71], v[42:43], v[22:23]
	v_pk_fma_f32 v[88:89], v[68:69], v[32:33], v[20:21]
	v_pk_fma_f32 v[84:85], v[66:67], v[36:37], v[18:19]
	s_cbranch_execz .LBB0_890

; __device__ __forceinline__ float sigmoidf_(float x) { return __builtin_amdgcn_rcpf(1.f + __builtin_amdgcn_exp2f(-1.44269504f * x)); }
;     __device__ __forceinline__ void operator()(f32x4 (&acc)[2][2][4][2], const Unit& u, int wr, int wc, int fr, int fq) const {
;     ...
;                 const size_t r = (size_t)(u.pm * 256 + ai * 128 + wr * 64 + m * 16 + fr); const int c = u.pn * 128 + wc * 32 + 8 * fq;
;                 const u32x4 gq = *(const u32x4*)(GT + r * 3072 + goff + c);
;                 float gf[8]; unpack8(gq, gf);
;                 const f32x4 g0 = {gf[0], gf[1], gf[2], gf[3]}, g1 = {gf[4], gf[5], gf[6], gf[7]};
;                 const f32x4 v0 = acc[ai][1][m][0], v1 = acc[ai][1][m][1]; f32x4 M0 = acc[ai][0][m][0], M1 = acc[ai][0][m][1];
;                 if (mode == 0) {
; #pragma unroll
;                     for (int i = 0; i < 4; ++i) { M0[i] = g0[i] * sigmoidf_(M0[i]) * v0[i]; M1[i] = g1[i] * sigmoidf_(M1[i]) * v1[i]; }
;                 } else { M0 += g0 * v0; M1 += g1 * v1; }
.LBB0_870:
	s_nop 1
	v_add_u32_e32 v18, 0xa0, v140
	v_mov_b64_e32 v[20:21], s[58:59]
	v_mad_i64_i32 v[20:21], s[0:1], v18, s97, v[20:21]
	v_lshl_add_u64 v[20:21], v[20:21], 0, s[6:7]
	v_lshl_add_u64 v[20:21], v[130:131], 1, v[20:21]
	s_and_b64 vcc, exec, s[42:43]
	s_mov_b64 s[0:1], -1
	s_waitcnt vmcnt(1)
	v_lshlrev_b32_e32 v30, 16, v176
	v_and_b32_e32 v31, 0xffff0000, v176
	v_lshlrev_b32_e32 v22, 16, v177
	v_and_b32_e32 v23, 0xffff0000, v177
	v_lshlrev_b32_e32 v24, 16, v178
	v_and_b32_e32 v25, 0xffff0000, v178
	v_lshlrev_b32_e32 v20, 16, v179
	v_and_b32_e32 v21, 0xffff0000, v179
	s_cbranch_vccnz .LBB0_891
	v_pk_fma_f32 v[70:71], v[56:57], v[22:23], v[16:17]
	v_pk_fma_f32 v[66:67], v[54:55], v[30:31], v[14:15]
	v_pk_fma_f32 v[72:73], v[52:53], v[20:21], v[12:13]
	v_pk_fma_f32 v[68:69], v[50:51], v[24:25], v[10:11]
	s_cbranch_execz .LBB0_892

; __device__ __forceinline__ float sigmoidf_(float x) { return __builtin_amdgcn_rcpf(1.f + __builtin_amdgcn_exp2f(-1.44269504f * x)); }
;     __device__ __forceinline__ void operator()(f32x4 (&acc)[2][2][4][2], const Unit& u, int wr, int wc, int fr, int fq) const {
;     ...
;                 const size_t r = (size_t)(u.pm * 256 + ai * 128 + wr * 64 + m * 16 + fr); const int c = u.pn * 128 + wc * 32 + 8 * fq;
;                 const u32x4 gq = *(const u32x4*)(GT + r * 3072 + goff + c);
;                 float gf[8]; unpack8(gq, gf);
;                 const f32x4 g0 = {gf[0], gf[1], gf[2], gf[3]}, g1 = {gf[4], gf[5], gf[6], gf[7]};
;                 const f32x4 v0 = acc[ai][1][m][0], v1 = acc[ai][1][m][1]; f32x4 M0 = acc[ai][0][m][0], M1 = acc[ai][0][m][1];
;                 if (mode == 0) {
; #pragma unroll
;                     for (int i = 0; i < 4; ++i) { M0[i] = g0[i] * sigmoidf_(M0[i]) * v0[i]; M1[i] = g1[i] * sigmoidf_(M1[i]) * v1[i]; }
;                 } else { M0 += g0 * v0; M1 += g1 * v1; }
.LBB0_874:
	s_nop 1
	v_add_u32_e32 v10, 0xb0, v140
	v_mov_b64_e32 v[12:13], s[58:59]
	v_mad_i64_i32 v[12:13], s[0:1], v10, s97, v[12:13]
	v_lshl_add_u64 v[12:13], v[12:13], 0, s[6:7]
	v_lshl_add_u64 v[12:13], v[130:131], 1, v[12:13]
	s_and_b64 vcc, exec, s[42:43]
	s_mov_b64 s[0:1], -1
	s_waitcnt vmcnt(0)
	v_lshlrev_b32_e32 v18, 16, v180
	v_and_b32_e32 v19, 0xffff0000, v180
	v_lshlrev_b32_e32 v14, 16, v181
	v_and_b32_e32 v15, 0xffff0000, v181
	v_lshlrev_b32_e32 v16, 16, v182
	v_and_b32_e32 v17, 0xffff0000, v182
	v_lshlrev_b32_e32 v12, 16, v183
	v_and_b32_e32 v13, 0xffff0000, v183
	s_cbranch_vccnz .LBB0_893
	v_pk_fma_f32 v[54:55], v[40:41], v[14:15], v[8:9]
	v_pk_fma_f32 v[50:51], v[38:39], v[18:19], v[6:7]
	v_pk_fma_f32 v[56:57], v[28:29], v[12:13], v[4:5]
	v_pk_fma_f32 v[52:53], v[26:27], v[16:17], v[2:3]
	s_cbranch_execz .LBB0_894

;     __device__ __forceinline__ void operator()(const f32x4 (&acc)[2][2][4][2], const Unit& u, int wr, int wc, int fr, int fq) const {
;         const TileRows tr(u.pm);
;         float* xb = tr.tb == 0 ? xc + (size_t)tr.b * CTXL * DM : out + ((size_t)tr.b * SEQ + (tr.tb - 1) * 256) * DM;
;         const float* gate = mods_l + (size_t)(tr.tb == 0 ? 8 : tr.b) * 6144 + gi * DM;
;         if (u.batch == 0) {
;             pg8::epi_foreach(acc, wr, wc, fr, fq, [&](int rl, int cl, const f32x4& v) {
;                 const int c = u.pn * 256 + cl; float* p = xb + (size_t)rl * DM + c;
;                 const f32x4 gt = *(const f32x4*)(gate + c); f32x4 xv = *(f32x4*)p; xv += gt * v; *(f32x4*)p = xv; });
;         } else {
;             float* pb = PB + (size_t)((u.batch - 1) * 32 + u.aux) * 65536;
;             pg8::epi_foreach(acc, wr, wc, fr, fq, [&](int rl, int cl, const f32x4& v) {
;                 const f32x4 gt = *(const f32x4*)(gate + u.pn * 256 + cl); *(f32x4*)(pb + rl * 256 + cl) = gt * v; });
.LBB0_1007:
	s_add_u32 s5, s47, s24
	s_addc_u32 s9, s48, s25
	s_add_u32 s8, s5, 0x2000
	s_addc_u32 s9, s9, 0
	s_mov_b64 s[24:25], -1
	s_and_b64 vcc, exec, s[0:1]
	s_cbranch_vccz .LBB0_1010
	s_lshl_b32 s0, s74, 5
	s_add_i32 s0, s75, s0
	s_sub_i32 s0, s0, 32
	s_ashr_i32 s1, s0, 31
	s_lshl_b64 s[0:1], s[0:1], 18
	s_add_u32 s0, s42, s0
	s_addc_u32 s1, s43, s1
	s_lshl_b32 s24, s73, 8
	s_ashr_i32 s25, s24, 31
	v_lshl_add_u32 v136, v146, 2, s31
	s_lshl_b64 s[24:25], s[24:25], 2
	s_add_u32 s24, s8, s24
	v_ashrrev_i32_e32 v137, 31, v136
	s_addc_u32 s25, s9, s25
	v_lshlrev_b64 v[138:139], 2, v[136:137]
	v_lshl_add_u64 v[136:137], s[24:25], 0, v[138:139]
	v_lshl_add_u32 v140, v147, 8, s2
	v_ashrrev_i32_e32 v141, 31, v140
	v_lshl_add_u64 v[152:153], v[140:141], 2, s[0:1]
	v_lshl_add_u64 v[152:153], v[152:153], 0, v[138:139]
	global_load_dwordx4 v[148:151], v[136:137], off
	global_load_dwordx4 v[156:159], v[136:137], off offset:64
	global_load_dwordx4 v[160:163], v[136:137], off offset:512
	global_load_dwordx4 v[164:167], v[136:137], off offset:576
	s_waitcnt vmcnt(0)
	v_pk_mul_f32 v[170:171], v[128:129], v[150:151]
	v_pk_mul_f32 v[168:169], v[126:127], v[148:149]
	global_store_dwordx4 v[152:153], v[168:171], off
	v_pk_mul_f32 v[174:175], v[124:125], v[158:159]
	v_pk_mul_f32 v[172:173], v[122:123], v[156:157]
	global_store_dwordx4 v[152:153], v[172:175], off offset:64
	v_pk_mul_f32 v[178:179], v[120:121], v[162:163]
	v_pk_mul_f32 v[176:177], v[118:119], v[160:161]
	global_store_dwordx4 v[152:153], v[176:179], off offset:512
	v_pk_mul_f32 v[182:183], v[116:117], v[166:167]
	v_pk_mul_f32 v[180:181], v[114:115], v[164:165]
	global_store_dwordx4 v[152:153], v[180:183], off offset:576
	s_mov_b32 s100, 0x4000
	s_mov_b32 s101, 0
	v_lshl_add_u64 v[152:153], v[152:153], 0, s[100:101]
	v_pk_mul_f32 v[186:187], v[112:113], v[150:151]
	v_pk_mul_f32 v[184:185], v[110:111], v[148:149]
	global_store_dwordx4 v[152:153], v[184:187], off
	v_pk_mul_f32 v[190:191], v[108:109], v[158:159]
	v_pk_mul_f32 v[188:189], v[106:107], v[156:157]
	global_store_dwordx4 v[152:153], v[188:191], off offset:64
	v_pk_mul_f32 v[194:195], v[104:105], v[162:163]
	v_pk_mul_f32 v[192:193], v[102:103], v[160:161]
	global_store_dwordx4 v[152:153], v[192:195], off offset:512
	v_pk_mul_f32 v[198:199], v[100:101], v[166:167]
	v_pk_mul_f32 v[196:197], v[98:99], v[164:165]
	global_store_dwordx4 v[152:153], v[196:199], off offset:576
	v_lshl_add_u64 v[152:153], v[152:153], 0, s[100:101]
	v_pk_mul_f32 v[170:171], v[96:97], v[150:151]
	v_pk_mul_f32 v[168:169], v[94:95], v[148:149]
	global_store_dwordx4 v[152:153], v[168:171], off
	v_pk_mul_f32 v[174:175], v[92:93], v[158:159]
	v_pk_mul_f32 v[172:173], v[90:91], v[156:157]
	global_store_dwordx4 v[152:153], v[172:175], off offset:64
	v_pk_mul_f32 v[178:179], v[88:89], v[162:163]
	v_pk_mul_f32 v[176:177], v[86:87], v[160:161]
	global_store_dwordx4 v[152:153], v[176:179], off offset:512
	v_pk_mul_f32 v[182:183], v[84:85], v[166:167]
	v_pk_mul_f32 v[180:181], v[82:83], v[164:165]
	global_store_dwordx4 v[152:153], v[180:183], off offset:576
	v_lshl_add_u64 v[152:153], v[152:153], 0, s[100:101]
	v_pk_mul_f32 v[186:187], v[80:81], v[150:151]
	v_pk_mul_f32 v[184:185], v[78:79], v[148:149]
	global_store_dwordx4 v[152:153], v[184:187], off
	v_pk_mul_f32 v[190:191], v[76:77], v[158:159]
	v_pk_mul_f32 v[188:189], v[74:75], v[156:157]
	global_store_dwordx4 v[152:153], v[188:191], off offset:64
	v_pk_mul_f32 v[194:195], v[72:73], v[162:163]
	v_pk_mul_f32 v[192:193], v[70:71], v[160:161]
	global_store_dwordx4 v[152:153], v[192:195], off offset:512
	v_pk_mul_f32 v[198:199], v[68:69], v[166:167]
	v_pk_mul_f32 v[196:197], v[66:67], v[164:165]
	global_store_dwordx4 v[152:153], v[196:199], off offset:576
	s_mov_b32 s100, 0x14000
	v_lshl_add_u64 v[152:153], v[152:153], 0, s[100:101]
	v_pk_mul_f32 v[170:171], v[64:65], v[150:151]
	v_pk_mul_f32 v[168:169], v[62:63], v[148:149]
	global_store_dwordx4 v[152:153], v[168:171], off
	v_pk_mul_f32 v[174:175], v[60:61], v[158:159]
	v_pk_mul_f32 v[172:173], v[58:59], v[156:157]
	global_store_dwordx4 v[152:153], v[172:175], off offset:64
	v_pk_mul_f32 v[178:179], v[56:57], v[162:163]
	v_pk_mul_f32 v[176:177], v[54:55], v[160:161]
	global_store_dwordx4 v[152:153], v[176:179], off offset:512
	v_pk_mul_f32 v[182:183], v[52:53], v[166:167]
	v_pk_mul_f32 v[180:181], v[50:51], v[164:165]
	global_store_dwordx4 v[152:153], v[180:183], off offset:576
	s_mov_b32 s100, 0x4000
	v_lshl_add_u64 v[152:153], v[152:153], 0, s[100:101]
	v_pk_mul_f32 v[186:187], v[48:49], v[150:151]
	v_pk_mul_f32 v[184:185], v[46:47], v[148:149]
	global_store_dwordx4 v[152:153], v[184:187], off
	v_pk_mul_f32 v[190:191], v[44:45], v[158:159]
	v_pk_mul_f32 v[188:189], v[42:43], v[156:157]
	global_store_dwordx4 v[152:153], v[188:191], off offset:64
	v_pk_mul_f32 v[194:195], v[40:41], v[162:163]
	v_pk_mul_f32 v[192:193], v[38:39], v[160:161]
	global_store_dwordx4 v[152:153], v[192:195], off offset:512
	v_pk_mul_f32 v[198:199], v[36:37], v[166:167]
	v_pk_mul_f32 v[196:197], v[34:35], v[164:165]
	global_store_dwordx4 v[152:153], v[196:199], off offset:576
	v_lshl_add_u64 v[152:153], v[152:153], 0, s[100:101]
	v_pk_mul_f32 v[170:171], v[32:33], v[150:151]
	v_pk_mul_f32 v[168:169], v[30:31], v[148:149]
	global_store_dwordx4 v[152:153], v[168:171], off
	v_pk_mul_f32 v[174:175], v[28:29], v[158:159]
	v_pk_mul_f32 v[172:173], v[26:27], v[156:157]
	global_store_dwordx4 v[152:153], v[172:175], off offset:64
	v_pk_mul_f32 v[178:179], v[24:25], v[162:163]
	v_pk_mul_f32 v[176:177], v[22:23], v[160:161]
	global_store_dwordx4 v[152:153], v[176:179], off offset:512
	v_pk_mul_f32 v[182:183], v[20:21], v[166:167]
	v_pk_mul_f32 v[180:181], v[18:19], v[164:165]
	global_store_dwordx4 v[152:153], v[180:183], off offset:576
	v_lshl_add_u64 v[152:153], v[152:153], 0, s[100:101]
	v_pk_mul_f32 v[186:187], v[16:17], v[150:151]
	v_pk_mul_f32 v[184:185], v[14:15], v[148:149]
	global_store_dwordx4 v[152:153], v[184:187], off
	v_pk_mul_f32 v[190:191], v[12:13], v[158:159]
	v_pk_mul_f32 v[188:189], v[10:11], v[156:157]
	global_store_dwordx4 v[152:153], v[188:191], off offset:64
	v_pk_mul_f32 v[194:195], v[8:9], v[162:163]
	v_pk_mul_f32 v[192:193], v[6:7], v[160:161]
	global_store_dwordx4 v[152:153], v[192:195], off offset:512
	v_pk_mul_f32 v[198:199], v[4:5], v[166:167]
	v_pk_mul_f32 v[196:197], v[2:3], v[164:165]
	global_store_dwordx4 v[152:153], v[196:199], off offset:576
	s_cbranch_execz .LBB0_1011

;     __device__ __forceinline__ void operator()(const f32x4 (&acc)[2][2][4][2], const Unit& u, int wr, int wc, int fr, int fq) const {
;         const TileRows tr(u.pm);
;         float* xb = tr.tb == 0 ? xc + (size_t)tr.b * CTXL * DM : out + ((size_t)tr.b * SEQ + (tr.tb - 1) * 256) * DM;
;         const float* gate = mods_l + (size_t)(tr.tb == 0 ? 8 : tr.b) * 6144 + gi * DM;
;         if (u.batch == 0) {
;             pg8::epi_foreach(acc, wr, wc, fr, fq, [&](int rl, int cl, const f32x4& v) {
;                 const int c = u.pn * 256 + cl; float* p = xb + (size_t)rl * DM + c;
;                 const f32x4 gt = *(const f32x4*)(gate + c); f32x4 xv = *(f32x4*)p; xv += gt * v; *(f32x4*)p = xv; });
.LBB0_1011:
	s_lshl_b32 s0, s73, 8
	v_add_u32_e32 v136, s69, v147
	s_or_b32 s0, s0, s31
	v_ashrrev_i32_e32 v137, 31, v136
	v_lshl_add_u32 v154, v146, 2, s0
	v_lshlrev_b64 v[138:139], 12, v[136:137]
	v_ashrrev_i32_e32 v155, 31, v154
	v_lshl_add_u64 v[138:139], s[44:45], 0, v[138:139]
	v_lshlrev_b64 v[140:141], 2, v[154:155]
	v_lshl_add_u64 v[156:157], v[138:139], 0, v[140:141]
	v_lshl_add_u64 v[138:139], s[8:9], 0, v[140:141]
	global_load_dwordx4 v[148:151], v[138:139], off
	global_load_dwordx4 v[152:155], v[138:139], off offset:64
	global_load_dwordx4 v[160:163], v[138:139], off offset:512
	global_load_dwordx4 v[164:167], v[138:139], off offset:576
	s_mov_b32 s100, 0x10000
	s_mov_b32 s101, 0
	v_lshl_add_u64 v[158:159], v[156:157], 0, s[100:101]
	v_lshl_add_u64 v[192:193], v[158:159], 0, s[100:101]
	v_lshl_add_u64 v[194:195], v[192:193], 0, s[100:101]
	s_mov_b32 s100, 0x50000
	v_lshl_add_u64 v[196:197], v[194:195], 0, s[100:101]
	s_mov_b32 s100, 0x10000
	v_lshl_add_u64 v[198:199], v[196:197], 0, s[100:101]
	v_lshl_add_u64 v[200:201], v[198:199], 0, s[100:101]
	v_lshl_add_u64 v[202:203], v[200:201], 0, s[100:101]
	global_load_dwordx4 v[168:171], v[156:157], off
	global_load_dwordx4 v[172:175], v[156:157], off offset:64
	global_load_dwordx4 v[176:179], v[156:157], off offset:512
	global_load_dwordx4 v[180:183], v[156:157], off offset:576
	global_load_dwordx4 v[184:187], v[158:159], off
	global_load_dwordx4 v[188:191], v[158:159], off offset:64
	global_load_dwordx4 v[136:139], v[158:159], off offset:512
	s_waitcnt vmcnt(6)
	v_pk_fma_f32 v[128:129], v[128:129], v[150:151], v[170:171]
	v_pk_fma_f32 v[126:127], v[126:127], v[148:149], v[168:169]
	global_store_dwordx4 v[156:157], v[126:129], off
	global_load_dwordx4 v[168:171], v[158:159], off offset:576
	s_waitcnt vmcnt(7)
	v_pk_fma_f32 v[124:125], v[124:125], v[154:155], v[174:175]
	v_pk_fma_f32 v[122:123], v[122:123], v[152:153], v[172:173]
	global_store_dwordx4 v[156:157], v[122:125], off offset:64
	global_load_dwordx4 v[172:175], v[192:193], off
	s_waitcnt vmcnt(8)
	v_pk_fma_f32 v[120:121], v[120:121], v[162:163], v[178:179]
	v_pk_fma_f32 v[118:119], v[118:119], v[160:161], v[176:177]
	global_store_dwordx4 v[156:157], v[118:121], off offset:512
	global_load_dwordx4 v[176:179], v[192:193], off offset:64
	s_waitcnt vmcnt(9)
	v_pk_fma_f32 v[116:117], v[116:117], v[166:167], v[182:183]
	v_pk_fma_f32 v[114:115], v[114:115], v[164:165], v[180:181]
	global_store_dwordx4 v[156:157], v[114:117], off offset:576
	global_load_dwordx4 v[180:183], v[192:193], off offset:512
	s_waitcnt vmcnt(10)
	v_pk_fma_f32 v[112:113], v[112:113], v[150:151], v[186:187]
	v_pk_fma_f32 v[110:111], v[110:111], v[148:149], v[184:185]
	global_store_dwordx4 v[158:159], v[110:113], off
	global_load_dwordx4 v[184:187], v[192:193], off offset:576
	s_waitcnt vmcnt(11)
	v_pk_fma_f32 v[108:109], v[108:109], v[154:155], v[190:191]
	v_pk_fma_f32 v[106:107], v[106:107], v[152:153], v[188:189]
	global_store_dwordx4 v[158:159], v[106:109], off offset:64
	global_load_dwordx4 v[188:191], v[194:195], off
	s_waitcnt vmcnt(12)
	v_pk_fma_f32 v[104:105], v[104:105], v[162:163], v[138:139]
	v_pk_fma_f32 v[102:103], v[102:103], v[160:161], v[136:137]
	global_store_dwordx4 v[158:159], v[102:105], off offset:512
	global_load_dwordx4 v[136:139], v[194:195], off offset:64
	s_waitcnt vmcnt(12)
	v_pk_fma_f32 v[100:101], v[100:101], v[166:167], v[170:171]
	v_pk_fma_f32 v[98:99], v[98:99], v[164:165], v[168:169]
	global_store_dwordx4 v[158:159], v[98:101], off offset:576
	global_load_dwordx4 v[168:171], v[194:195], off offset:512
	s_waitcnt vmcnt(12)
	v_pk_fma_f32 v[96:97], v[96:97], v[150:151], v[174:175]
	v_pk_fma_f32 v[94:95], v[94:95], v[148:149], v[172:173]
	global_store_dwordx4 v[192:193], v[94:97], off
	global_load_dwordx4 v[172:175], v[194:195], off offset:576
	s_waitcnt vmcnt(12)
	v_pk_fma_f32 v[92:93], v[92:93], v[154:155], v[178:179]
	v_pk_fma_f32 v[90:91], v[90:91], v[152:153], v[176:177]
	global_store_dwordx4 v[192:193], v[90:93], off offset:64
	global_load_dwordx4 v[176:179], v[196:197], off
	s_waitcnt vmcnt(12)
	v_pk_fma_f32 v[88:89], v[88:89], v[162:163], v[182:183]
	v_pk_fma_f32 v[86:87], v[86:87], v[160:161], v[180:181]
	global_store_dwordx4 v[192:193], v[86:89], off offset:512
	global_load_dwordx4 v[180:183], v[196:197], off offset:64
	s_waitcnt vmcnt(12)
	v_pk_fma_f32 v[84:85], v[84:85], v[166:167], v[186:187]
	v_pk_fma_f32 v[82:83], v[82:83], v[164:165], v[184:185]
	global_store_dwordx4 v[192:193], v[82:85], off offset:576
	global_load_dwordx4 v[184:187], v[196:197], off offset:512
	s_waitcnt vmcnt(12)
;     __device__ __forceinline__ void operator()(const f32x4 (&acc)[2][2][4][2], const Unit& u, int wr, int wc, int fr, int fq) const {
;     ...
;         if (u.batch == 0) {
;             pg8::epi_foreach(acc, wr, wc, fr, fq, [&](int rl, int cl, const f32x4& v) {
;                 const int c = u.pn * 256 + cl; float* p = xb + (size_t)rl * DM + c;
;                 const f32x4 gt = *(const f32x4*)(gate + c); f32x4 xv = *(f32x4*)p; xv += gt * v; *(f32x4*)p = xv; });
	v_pk_fma_f32 v[80:81], v[80:81], v[150:151], v[190:191]
	v_pk_fma_f32 v[78:79], v[78:79], v[148:149], v[188:189]
	global_store_dwordx4 v[194:195], v[78:81], off
	global_load_dwordx4 v[188:191], v[196:197], off offset:576
	s_waitcnt vmcnt(12)
	v_pk_fma_f32 v[76:77], v[76:77], v[154:155], v[138:139]
	v_pk_fma_f32 v[74:75], v[74:75], v[152:153], v[136:137]
	global_store_dwordx4 v[194:195], v[74:77], off offset:64
	global_load_dwordx4 v[136:139], v[198:199], off
	s_waitcnt vmcnt(12)
	v_pk_fma_f32 v[72:73], v[72:73], v[162:163], v[170:171]
	v_pk_fma_f32 v[70:71], v[70:71], v[160:161], v[168:169]
	global_store_dwordx4 v[194:195], v[70:73], off offset:512
	global_load_dwordx4 v[168:171], v[198:199], off offset:64
	s_waitcnt vmcnt(12)
	v_pk_fma_f32 v[68:69], v[68:69], v[166:167], v[174:175]
	v_pk_fma_f32 v[66:67], v[66:67], v[164:165], v[172:173]
	global_store_dwordx4 v[194:195], v[66:69], off offset:576
	global_load_dwordx4 v[172:175], v[198:199], off offset:512
	s_waitcnt vmcnt(12)
	v_pk_fma_f32 v[64:65], v[64:65], v[150:151], v[178:179]
	v_pk_fma_f32 v[62:63], v[62:63], v[148:149], v[176:177]
	global_store_dwordx4 v[196:197], v[62:65], off
	global_load_dwordx4 v[176:179], v[198:199], off offset:576
	s_waitcnt vmcnt(12)
	v_pk_fma_f32 v[60:61], v[60:61], v[154:155], v[182:183]
	v_pk_fma_f32 v[58:59], v[58:59], v[152:153], v[180:181]
	global_store_dwordx4 v[196:197], v[58:61], off offset:64
	global_load_dwordx4 v[180:183], v[200:201], off
	s_waitcnt vmcnt(12)
	v_pk_fma_f32 v[56:57], v[56:57], v[162:163], v[186:187]
	v_pk_fma_f32 v[54:55], v[54:55], v[160:161], v[184:185]
	global_store_dwordx4 v[196:197], v[54:57], off offset:512
	global_load_dwordx4 v[184:187], v[200:201], off offset:64
	s_waitcnt vmcnt(12)
	v_pk_fma_f32 v[52:53], v[52:53], v[166:167], v[190:191]
	v_pk_fma_f32 v[50:51], v[50:51], v[164:165], v[188:189]
	global_store_dwordx4 v[196:197], v[50:53], off offset:576
	global_load_dwordx4 v[188:191], v[200:201], off offset:512
	s_waitcnt vmcnt(12)
	v_pk_fma_f32 v[48:49], v[48:49], v[150:151], v[138:139]
	v_pk_fma_f32 v[46:47], v[46:47], v[148:149], v[136:137]
	global_store_dwordx4 v[198:199], v[46:49], off
	global_load_dwordx4 v[136:139], v[200:201], off offset:576
	s_waitcnt vmcnt(12)
	v_pk_fma_f32 v[44:45], v[44:45], v[154:155], v[170:171]
	v_pk_fma_f32 v[42:43], v[42:43], v[152:153], v[168:169]
	global_store_dwordx4 v[198:199], v[42:45], off offset:64
	global_load_dwordx4 v[168:171], v[202:203], off
	s_waitcnt vmcnt(12)
	v_pk_fma_f32 v[40:41], v[40:41], v[162:163], v[174:175]
	v_pk_fma_f32 v[38:39], v[38:39], v[160:161], v[172:173]
	global_store_dwordx4 v[198:199], v[38:41], off offset:512
	global_load_dwordx4 v[172:175], v[202:203], off offset:64
	s_waitcnt vmcnt(12)
	v_pk_fma_f32 v[36:37], v[36:37], v[166:167], v[178:179]
	v_pk_fma_f32 v[34:35], v[34:35], v[164:165], v[176:177]
	global_store_dwordx4 v[198:199], v[34:37], off offset:576
	global_load_dwordx4 v[176:179], v[202:203], off offset:512
	s_waitcnt vmcnt(12)
	v_pk_fma_f32 v[32:33], v[32:33], v[150:151], v[182:183]
	v_pk_fma_f32 v[30:31], v[30:31], v[148:149], v[180:181]
	global_store_dwordx4 v[200:201], v[30:33], off
	global_load_dwordx4 v[180:183], v[202:203], off offset:576
	s_waitcnt vmcnt(12)
	v_pk_fma_f32 v[28:29], v[28:29], v[154:155], v[186:187]
	v_pk_fma_f32 v[26:27], v[26:27], v[152:153], v[184:185]
	global_store_dwordx4 v[200:201], v[26:29], off offset:64
	s_waitcnt vmcnt(11)
	v_pk_fma_f32 v[24:25], v[24:25], v[162:163], v[190:191]
	v_pk_fma_f32 v[22:23], v[22:23], v[160:161], v[188:189]
	global_store_dwordx4 v[200:201], v[22:25], off offset:512
	s_waitcnt vmcnt(10)
	v_pk_fma_f32 v[20:21], v[20:21], v[166:167], v[138:139]
	v_pk_fma_f32 v[18:19], v[18:19], v[164:165], v[136:137]
	global_store_dwordx4 v[200:201], v[18:21], off offset:576
	s_waitcnt vmcnt(9)
	v_pk_fma_f32 v[16:17], v[16:17], v[150:151], v[170:171]
	v_pk_fma_f32 v[14:15], v[14:15], v[148:149], v[168:169]
	global_store_dwordx4 v[202:203], v[14:17], off
	s_waitcnt vmcnt(8)
	v_pk_fma_f32 v[12:13], v[12:13], v[154:155], v[174:175]
	v_pk_fma_f32 v[10:11], v[10:11], v[152:153], v[172:173]
	global_store_dwordx4 v[202:203], v[10:13], off offset:64
	s_waitcnt vmcnt(7)
	v_pk_fma_f32 v[8:9], v[8:9], v[162:163], v[178:179]
	v_pk_fma_f32 v[6:7], v[6:7], v[160:161], v[176:177]
	global_store_dwordx4 v[202:203], v[6:9], off offset:512
	s_waitcnt vmcnt(6)
	v_pk_fma_f32 v[4:5], v[4:5], v[166:167], v[182:183]
	v_pk_fma_f32 v[2:3], v[2:3], v[164:165], v[180:181]
	global_store_dwordx4 v[202:203], v[2:5], off offset:576
	s_and_b64 vcc, exec, s[40:41]
	s_mov_b64 s[0:1], -1
	s_cbranch_vccnz .LBB0_989

;     __device__ __forceinline__ void operator()(const f32x4 (&acc)[2][2][4][2], const Unit& u, int wr, int wc, int fr, int fq) const {
;         const TileRows tr(u.pm);
;         float* xb = tr.tb == 0 ? xc + (size_t)tr.b * CTXL * DM : out + ((size_t)tr.b * SEQ + (tr.tb - 1) * 256) * DM;
;         const float* gate = mods_l + (size_t)(tr.tb == 0 ? 8 : tr.b) * 6144 + gi * DM;
;         if (u.batch == 0) {
;             pg8::epi_foreach(acc, wr, wc, fr, fq, [&](int rl, int cl, const f32x4& v) {
;                 const int c = u.pn * 256 + cl; float* p = xb + (size_t)rl * DM + c;
;                 const f32x4 gt = *(const f32x4*)(gate + c); f32x4 xv = *(f32x4*)p; xv += gt * v; *(f32x4*)p = xv; });
;         } else {
;             float* pb = PB + (size_t)((u.batch - 1) * 32 + u.aux) * 65536;
;             pg8::epi_foreach(acc, wr, wc, fr, fq, [&](int rl, int cl, const f32x4& v) {
;                 const f32x4 gt = *(const f32x4*)(gate + u.pn * 256 + cl); *(f32x4*)(pb + rl * 256 + cl) = gt * v; });
.LBB0_1041:
	s_add_u32 s0, s47, s24
	s_addc_u32 s1, s48, s25
	s_add_u32 s0, s0, 0x2000
	s_addc_u32 s1, s1, 0
	s_lshl_b32 s8, s8, 8
	s_cmp_lg_u32 s9, 0
	v_lshl_add_u32 v136, v136, 2, s56
	s_cbranch_scc0 .LBB0_1048
	s_ashr_i32 s9, s8, 31
	s_lshl_b64 s[24:25], s[8:9], 2
	s_add_u32 s24, s0, s24
	v_ashrrev_i32_e32 v137, 31, v136
	s_addc_u32 s25, s1, s25
	v_lshlrev_b64 v[140:141], 2, v[136:137]
	v_lshl_add_u64 v[138:139], s[24:25], 0, v[140:141]
	v_lshl_add_u32 v142, v148, 8, s63
	v_ashrrev_i32_e32 v143, 31, v142
	v_lshl_add_u64 v[154:155], v[142:143], 2, s[42:43]
	v_lshl_add_u64 v[154:155], v[154:155], 0, v[140:141]
	global_load_dwordx4 v[156:159], v[138:139], off
	global_load_dwordx4 v[160:163], v[138:139], off offset:64
	global_load_dwordx4 v[164:167], v[138:139], off offset:512
	global_load_dwordx4 v[168:171], v[138:139], off offset:576
	s_waitcnt vmcnt(0)
	v_pk_mul_f32 v[174:175], v[128:129], v[158:159]
	v_pk_mul_f32 v[172:173], v[126:127], v[156:157]
	global_store_dwordx4 v[154:155], v[172:175], off
	v_pk_mul_f32 v[178:179], v[124:125], v[162:163]
	v_pk_mul_f32 v[176:177], v[122:123], v[160:161]
	global_store_dwordx4 v[154:155], v[176:179], off offset:64
	v_pk_mul_f32 v[182:183], v[120:121], v[166:167]
	v_pk_mul_f32 v[180:181], v[118:119], v[164:165]
	global_store_dwordx4 v[154:155], v[180:183], off offset:512
	v_pk_mul_f32 v[186:187], v[116:117], v[170:171]
	v_pk_mul_f32 v[184:185], v[114:115], v[168:169]
	global_store_dwordx4 v[154:155], v[184:187], off offset:576
	s_mov_b32 s100, 0x4000
	s_mov_b32 s101, 0
	v_lshl_add_u64 v[154:155], v[154:155], 0, s[100:101]
	v_pk_mul_f32 v[190:191], v[112:113], v[158:159]
	v_pk_mul_f32 v[188:189], v[110:111], v[156:157]
	global_store_dwordx4 v[154:155], v[188:191], off
	v_pk_mul_f32 v[194:195], v[108:109], v[162:163]
	v_pk_mul_f32 v[192:193], v[106:107], v[160:161]
	global_store_dwordx4 v[154:155], v[192:195], off offset:64
	v_pk_mul_f32 v[198:199], v[104:105], v[166:167]
	v_pk_mul_f32 v[196:197], v[102:103], v[164:165]
	global_store_dwordx4 v[154:155], v[196:199], off offset:512
	v_pk_mul_f32 v[202:203], v[100:101], v[170:171]
	v_pk_mul_f32 v[200:201], v[98:99], v[168:169]
	global_store_dwordx4 v[154:155], v[200:203], off offset:576
	v_lshl_add_u64 v[154:155], v[154:155], 0, s[100:101]
	v_pk_mul_f32 v[174:175], v[96:97], v[158:159]
	v_pk_mul_f32 v[172:173], v[94:95], v[156:157]
	global_store_dwordx4 v[154:155], v[172:175], off
	v_pk_mul_f32 v[178:179], v[92:93], v[162:163]
	v_pk_mul_f32 v[176:177], v[90:91], v[160:161]
	global_store_dwordx4 v[154:155], v[176:179], off offset:64
	v_pk_mul_f32 v[182:183], v[88:89], v[166:167]
	v_pk_mul_f32 v[180:181], v[86:87], v[164:165]
	global_store_dwordx4 v[154:155], v[180:183], off offset:512
	v_pk_mul_f32 v[186:187], v[84:85], v[170:171]
	v_pk_mul_f32 v[184:185], v[82:83], v[168:169]
	global_store_dwordx4 v[154:155], v[184:187], off offset:576
	v_lshl_add_u64 v[154:155], v[154:155], 0, s[100:101]
	v_pk_mul_f32 v[190:191], v[80:81], v[158:159]
	v_pk_mul_f32 v[188:189], v[78:79], v[156:157]
	global_store_dwordx4 v[154:155], v[188:191], off
	v_pk_mul_f32 v[194:195], v[76:77], v[162:163]
	v_pk_mul_f32 v[192:193], v[74:75], v[160:161]
	global_store_dwordx4 v[154:155], v[192:195], off offset:64
	v_pk_mul_f32 v[198:199], v[72:73], v[166:167]
	v_pk_mul_f32 v[196:197], v[70:71], v[164:165]
	global_store_dwordx4 v[154:155], v[196:199], off offset:512
	v_pk_mul_f32 v[202:203], v[68:69], v[170:171]
	v_pk_mul_f32 v[200:201], v[66:67], v[168:169]
	global_store_dwordx4 v[154:155], v[200:203], off offset:576
	s_mov_b32 s100, 0x14000
	v_lshl_add_u64 v[154:155], v[154:155], 0, s[100:101]
	v_pk_mul_f32 v[174:175], v[64:65], v[158:159]
	v_pk_mul_f32 v[172:173], v[62:63], v[156:157]
	global_store_dwordx4 v[154:155], v[172:175], off
	v_pk_mul_f32 v[178:179], v[60:61], v[162:163]
	v_pk_mul_f32 v[176:177], v[58:59], v[160:161]
	global_store_dwordx4 v[154:155], v[176:179], off offset:64
	v_pk_mul_f32 v[182:183], v[56:57], v[166:167]
	v_pk_mul_f32 v[180:181], v[54:55], v[164:165]
	global_store_dwordx4 v[154:155], v[180:183], off offset:512
	v_pk_mul_f32 v[186:187], v[52:53], v[170:171]
	v_pk_mul_f32 v[184:185], v[50:51], v[168:169]
	global_store_dwordx4 v[154:155], v[184:187], off offset:576
	s_mov_b32 s100, 0x4000
	v_lshl_add_u64 v[154:155], v[154:155], 0, s[100:101]
	v_pk_mul_f32 v[190:191], v[48:49], v[158:159]
	v_pk_mul_f32 v[188:189], v[46:47], v[156:157]
	global_store_dwordx4 v[154:155], v[188:191], off
	v_pk_mul_f32 v[194:195], v[44:45], v[162:163]
	v_pk_mul_f32 v[192:193], v[42:43], v[160:161]
	global_store_dwordx4 v[154:155], v[192:195], off offset:64
	v_pk_mul_f32 v[198:199], v[40:41], v[166:167]
	v_pk_mul_f32 v[196:197], v[38:39], v[164:165]
	global_store_dwordx4 v[154:155], v[196:199], off offset:512
	v_pk_mul_f32 v[202:203], v[36:37], v[170:171]
	v_pk_mul_f32 v[200:201], v[34:35], v[168:169]
	global_store_dwordx4 v[154:155], v[200:203], off offset:576
	v_lshl_add_u64 v[154:155], v[154:155], 0, s[100:101]
	v_pk_mul_f32 v[174:175], v[32:33], v[158:159]
	v_pk_mul_f32 v[172:173], v[30:31], v[156:157]
	global_store_dwordx4 v[154:155], v[172:175], off
	v_pk_mul_f32 v[178:179], v[28:29], v[162:163]
	v_pk_mul_f32 v[176:177], v[26:27], v[160:161]
	global_store_dwordx4 v[154:155], v[176:179], off offset:64
	v_pk_mul_f32 v[182:183], v[24:25], v[166:167]
	v_pk_mul_f32 v[180:181], v[22:23], v[164:165]
	global_store_dwordx4 v[154:155], v[180:183], off offset:512
	v_pk_mul_f32 v[186:187], v[20:21], v[170:171]
	v_pk_mul_f32 v[184:185], v[18:19], v[168:169]
	global_store_dwordx4 v[154:155], v[184:187], off offset:576
	v_lshl_add_u64 v[154:155], v[154:155], 0, s[100:101]
	v_pk_mul_f32 v[190:191], v[16:17], v[158:159]
	v_pk_mul_f32 v[188:189], v[14:15], v[156:157]
	global_store_dwordx4 v[154:155], v[188:191], off
	v_pk_mul_f32 v[194:195], v[12:13], v[162:163]
	v_pk_mul_f32 v[192:193], v[10:11], v[160:161]
	global_store_dwordx4 v[154:155], v[192:195], off offset:64
	v_pk_mul_f32 v[198:199], v[8:9], v[166:167]
	v_pk_mul_f32 v[196:197], v[6:7], v[164:165]
	global_store_dwordx4 v[154:155], v[196:199], off offset:512
	v_pk_mul_f32 v[202:203], v[4:5], v[170:171]
	v_pk_mul_f32 v[200:201], v[2:3], v[168:169]
	global_store_dwordx4 v[154:155], v[200:203], off offset:576
	s_cbranch_execnz .LBB0_1044
;     __device__ __forceinline__ void operator()(const f32x4 (&acc)[2][2][4][2], const Unit& u, int wr, int wc, int fr, int fq) const {
;         const TileRows tr(u.pm);
;         float* xb = tr.tb == 0 ? xc + (size_t)tr.b * CTXL * DM : out + ((size_t)tr.b * SEQ + (tr.tb - 1) * 256) * DM;
;         const float* gate = mods_l + (size_t)(tr.tb == 0 ? 8 : tr.b) * 6144 + gi * DM;
;         if (u.batch == 0) {
;             pg8::epi_foreach(acc, wr, wc, fr, fq, [&](int rl, int cl, const f32x4& v) {
;                 const int c = u.pn * 256 + cl; float* p = xb + (size_t)rl * DM + c;
;                 const f32x4 gt = *(const f32x4*)(gate + c); f32x4 xv = *(f32x4*)p; xv += gt * v; *(f32x4*)p = xv; });
.LBB0_1043:
	s_nop 0
	v_add_u32_e32 v138, s33, v148
	v_ashrrev_i32_e32 v139, 31, v138
	v_add_u32_e32 v142, s8, v136
	v_lshlrev_b64 v[140:141], 12, v[138:139]
	v_ashrrev_i32_e32 v143, 31, v142
	v_lshl_add_u64 v[136:137], s[44:45], 0, v[140:141]
	v_lshlrev_b64 v[140:141], 2, v[142:143]
	v_lshl_add_u64 v[156:157], v[136:137], 0, v[140:141]
	v_lshl_add_u64 v[136:137], s[0:1], 0, v[140:141]
	global_load_dwordx4 v[140:143], v[136:137], off
	global_load_dwordx4 v[148:151], v[136:137], off offset:64
	global_load_dwordx4 v[152:155], v[136:137], off offset:512
	global_load_dwordx4 v[160:163], v[136:137], off offset:576
	s_mov_b32 s100, 0x10000
	s_mov_b32 s101, 0
	v_lshl_add_u64 v[158:159], v[156:157], 0, s[100:101]
	v_lshl_add_u64 v[192:193], v[158:159], 0, s[100:101]
	v_lshl_add_u64 v[194:195], v[192:193], 0, s[100:101]
	s_mov_b32 s100, 0x50000
	v_lshl_add_u64 v[196:197], v[194:195], 0, s[100:101]
	s_mov_b32 s100, 0x10000
	v_lshl_add_u64 v[198:199], v[196:197], 0, s[100:101]
	v_lshl_add_u64 v[200:201], v[198:199], 0, s[100:101]
	v_lshl_add_u64 v[202:203], v[200:201], 0, s[100:101]
	global_load_dwordx4 v[164:167], v[156:157], off
	global_load_dwordx4 v[168:171], v[156:157], off offset:64
	global_load_dwordx4 v[172:175], v[156:157], off offset:512
	global_load_dwordx4 v[176:179], v[156:157], off offset:576
	global_load_dwordx4 v[180:183], v[158:159], off
	global_load_dwordx4 v[184:187], v[158:159], off offset:64
	global_load_dwordx4 v[188:191], v[158:159], off offset:512
	global_load_dwordx4 v[136:139], v[158:159], off offset:576
	s_waitcnt vmcnt(7)
	v_pk_fma_f32 v[128:129], v[128:129], v[142:143], v[166:167]
	v_pk_fma_f32 v[126:127], v[126:127], v[140:141], v[164:165]
	global_store_dwordx4 v[156:157], v[126:129], off
	global_load_dwordx4 v[164:167], v[192:193], off
	s_waitcnt vmcnt(8)
	v_pk_fma_f32 v[124:125], v[124:125], v[150:151], v[170:171]
	v_pk_fma_f32 v[122:123], v[122:123], v[148:149], v[168:169]
	global_store_dwordx4 v[156:157], v[122:125], off offset:64
	global_load_dwordx4 v[168:171], v[192:193], off offset:64
	s_waitcnt vmcnt(9)
	v_pk_fma_f32 v[120:121], v[120:121], v[154:155], v[174:175]
	v_pk_fma_f32 v[118:119], v[118:119], v[152:153], v[172:173]
	global_store_dwordx4 v[156:157], v[118:121], off offset:512
	global_load_dwordx4 v[172:175], v[192:193], off offset:512
	s_waitcnt vmcnt(10)
	v_pk_fma_f32 v[116:117], v[116:117], v[162:163], v[178:179]
	v_pk_fma_f32 v[114:115], v[114:115], v[160:161], v[176:177]
	global_store_dwordx4 v[156:157], v[114:117], off offset:576
	global_load_dwordx4 v[176:179], v[192:193], off offset:576
	s_waitcnt vmcnt(11)
	v_pk_fma_f32 v[112:113], v[112:113], v[142:143], v[182:183]
	v_pk_fma_f32 v[110:111], v[110:111], v[140:141], v[180:181]
	global_store_dwordx4 v[158:159], v[110:113], off
	global_load_dwordx4 v[180:183], v[194:195], off
	s_waitcnt vmcnt(12)
	v_pk_fma_f32 v[108:109], v[108:109], v[150:151], v[186:187]
	v_pk_fma_f32 v[106:107], v[106:107], v[148:149], v[184:185]
	global_store_dwordx4 v[158:159], v[106:109], off offset:64
	global_load_dwordx4 v[184:187], v[194:195], off offset:64
	s_waitcnt vmcnt(13)
	v_pk_fma_f32 v[104:105], v[104:105], v[154:155], v[190:191]
	v_pk_fma_f32 v[102:103], v[102:103], v[152:153], v[188:189]
	global_store_dwordx4 v[158:159], v[102:105], off offset:512
	global_load_dwordx4 v[188:191], v[194:195], off offset:512
	s_waitcnt vmcnt(14)
	v_pk_fma_f32 v[100:101], v[100:101], v[162:163], v[138:139]
	v_pk_fma_f32 v[98:99], v[98:99], v[160:161], v[136:137]
	global_store_dwordx4 v[158:159], v[98:101], off offset:576
	global_load_dwordx4 v[136:139], v[194:195], off offset:576
	s_waitcnt vmcnt(14)
	v_pk_fma_f32 v[96:97], v[96:97], v[142:143], v[166:167]
	v_pk_fma_f32 v[94:95], v[94:95], v[140:141], v[164:165]
	global_store_dwordx4 v[192:193], v[94:97], off
	global_load_dwordx4 v[164:167], v[196:197], off
	s_waitcnt vmcnt(14)
	v_pk_fma_f32 v[92:93], v[92:93], v[150:151], v[170:171]
	v_pk_fma_f32 v[90:91], v[90:91], v[148:149], v[168:169]
	global_store_dwordx4 v[192:193], v[90:93], off offset:64
	global_load_dwordx4 v[168:171], v[196:197], off offset:64
	s_waitcnt vmcnt(14)
	v_pk_fma_f32 v[88:89], v[88:89], v[154:155], v[174:175]
	v_pk_fma_f32 v[86:87], v[86:87], v[152:153], v[172:173]
	global_store_dwordx4 v[192:193], v[86:89], off offset:512
	global_load_dwordx4 v[172:175], v[196:197], off offset:512
	s_waitcnt vmcnt(14)
	v_pk_fma_f32 v[84:85], v[84:85], v[162:163], v[178:179]
	v_pk_fma_f32 v[82:83], v[82:83], v[160:161], v[176:177]
	global_store_dwordx4 v[192:193], v[82:85], off offset:576
	global_load_dwordx4 v[176:179], v[196:197], off offset:576
	s_waitcnt vmcnt(14)
;     __device__ __forceinline__ void operator()(const f32x4 (&acc)[2][2][4][2], const Unit& u, int wr, int wc, int fr, int fq) const {
;     ...
;         if (u.batch == 0) {
;             pg8::epi_foreach(acc, wr, wc, fr, fq, [&](int rl, int cl, const f32x4& v) {
;                 const int c = u.pn * 256 + cl; float* p = xb + (size_t)rl * DM + c;
;                 const f32x4 gt = *(const f32x4*)(gate + c); f32x4 xv = *(f32x4*)p; xv += gt * v; *(f32x4*)p = xv; });
	v_pk_fma_f32 v[80:81], v[80:81], v[142:143], v[182:183]
	v_pk_fma_f32 v[78:79], v[78:79], v[140:141], v[180:181]
	global_store_dwordx4 v[194:195], v[78:81], off
	global_load_dwordx4 v[180:183], v[198:199], off
	s_waitcnt vmcnt(14)
	v_pk_fma_f32 v[76:77], v[76:77], v[150:151], v[186:187]
	v_pk_fma_f32 v[74:75], v[74:75], v[148:149], v[184:185]
	global_store_dwordx4 v[194:195], v[74:77], off offset:64
	global_load_dwordx4 v[184:187], v[198:199], off offset:64
	s_waitcnt vmcnt(14)
	v_pk_fma_f32 v[72:73], v[72:73], v[154:155], v[190:191]
	v_pk_fma_f32 v[70:71], v[70:71], v[152:153], v[188:189]
	global_store_dwordx4 v[194:195], v[70:73], off offset:512
	global_load_dwordx4 v[188:191], v[198:199], off offset:512
	s_waitcnt vmcnt(14)
	v_pk_fma_f32 v[68:69], v[68:69], v[162:163], v[138:139]
	v_pk_fma_f32 v[66:67], v[66:67], v[160:161], v[136:137]
	global_store_dwordx4 v[194:195], v[66:69], off offset:576
	global_load_dwordx4 v[136:139], v[198:199], off offset:576
	s_waitcnt vmcnt(14)
	v_pk_fma_f32 v[64:65], v[64:65], v[142:143], v[166:167]
	v_pk_fma_f32 v[62:63], v[62:63], v[140:141], v[164:165]
	global_store_dwordx4 v[196:197], v[62:65], off
	global_load_dwordx4 v[164:167], v[200:201], off
	s_waitcnt vmcnt(14)
	v_pk_fma_f32 v[60:61], v[60:61], v[150:151], v[170:171]
	v_pk_fma_f32 v[58:59], v[58:59], v[148:149], v[168:169]
	global_store_dwordx4 v[196:197], v[58:61], off offset:64
	global_load_dwordx4 v[168:171], v[200:201], off offset:64
	s_waitcnt vmcnt(14)
	v_pk_fma_f32 v[56:57], v[56:57], v[154:155], v[174:175]
	v_pk_fma_f32 v[54:55], v[54:55], v[152:153], v[172:173]
	global_store_dwordx4 v[196:197], v[54:57], off offset:512
	global_load_dwordx4 v[172:175], v[200:201], off offset:512
	s_waitcnt vmcnt(14)
	v_pk_fma_f32 v[52:53], v[52:53], v[162:163], v[178:179]
	v_pk_fma_f32 v[50:51], v[50:51], v[160:161], v[176:177]
	global_store_dwordx4 v[196:197], v[50:53], off offset:576
	global_load_dwordx4 v[176:179], v[200:201], off offset:576
	s_waitcnt vmcnt(14)
	v_pk_fma_f32 v[48:49], v[48:49], v[142:143], v[182:183]
	v_pk_fma_f32 v[46:47], v[46:47], v[140:141], v[180:181]
	global_store_dwordx4 v[198:199], v[46:49], off
	global_load_dwordx4 v[180:183], v[202:203], off
	s_waitcnt vmcnt(14)
	v_pk_fma_f32 v[44:45], v[44:45], v[150:151], v[186:187]
	v_pk_fma_f32 v[42:43], v[42:43], v[148:149], v[184:185]
	global_store_dwordx4 v[198:199], v[42:45], off offset:64
	global_load_dwordx4 v[184:187], v[202:203], off offset:64
	s_waitcnt vmcnt(14)
	v_pk_fma_f32 v[40:41], v[40:41], v[154:155], v[190:191]
	v_pk_fma_f32 v[38:39], v[38:39], v[152:153], v[188:189]
	global_store_dwordx4 v[198:199], v[38:41], off offset:512
	global_load_dwordx4 v[188:191], v[202:203], off offset:512
	s_waitcnt vmcnt(14)
	v_pk_fma_f32 v[36:37], v[36:37], v[162:163], v[138:139]
	v_pk_fma_f32 v[34:35], v[34:35], v[160:161], v[136:137]
	global_store_dwordx4 v[198:199], v[34:37], off offset:576
	global_load_dwordx4 v[136:139], v[202:203], off offset:576
	s_waitcnt vmcnt(14)
	v_pk_fma_f32 v[32:33], v[32:33], v[142:143], v[166:167]
	v_pk_fma_f32 v[30:31], v[30:31], v[140:141], v[164:165]
	global_store_dwordx4 v[200:201], v[30:33], off
	s_waitcnt vmcnt(13)
	v_pk_fma_f32 v[28:29], v[28:29], v[150:151], v[170:171]
	v_pk_fma_f32 v[26:27], v[26:27], v[148:149], v[168:169]
	global_store_dwordx4 v[200:201], v[26:29], off offset:64
	s_waitcnt vmcnt(12)
	v_pk_fma_f32 v[24:25], v[24:25], v[154:155], v[174:175]
	v_pk_fma_f32 v[22:23], v[22:23], v[152:153], v[172:173]
	global_store_dwordx4 v[200:201], v[22:25], off offset:512
	s_waitcnt vmcnt(11)
	v_pk_fma_f32 v[20:21], v[20:21], v[162:163], v[178:179]
	v_pk_fma_f32 v[18:19], v[18:19], v[160:161], v[176:177]
	global_store_dwordx4 v[200:201], v[18:21], off offset:576
	s_waitcnt vmcnt(10)
	v_pk_fma_f32 v[16:17], v[16:17], v[142:143], v[182:183]
	v_pk_fma_f32 v[14:15], v[14:15], v[140:141], v[180:181]
	global_store_dwordx4 v[202:203], v[14:17], off
	s_waitcnt vmcnt(9)
	v_pk_fma_f32 v[12:13], v[12:13], v[150:151], v[186:187]
	v_pk_fma_f32 v[10:11], v[10:11], v[148:149], v[184:185]
	global_store_dwordx4 v[202:203], v[10:13], off offset:64
	s_waitcnt vmcnt(8)
	v_pk_fma_f32 v[8:9], v[8:9], v[154:155], v[190:191]
	v_pk_fma_f32 v[6:7], v[6:7], v[152:153], v[188:189]
	global_store_dwordx4 v[202:203], v[6:9], off offset:512
	s_waitcnt vmcnt(7)
	v_pk_fma_f32 v[4:5], v[4:5], v[162:163], v[138:139]
	v_pk_fma_f32 v[2:3], v[2:3], v[160:161], v[136:137]
	global_store_dwordx4 v[202:203], v[2:5], off offset:576

;     __device__ __forceinline__ void operator()(const f32x4 (&acc)[2][2][4][2], const Unit& u, int wr, int wc, int fr, int fq) const {
;         const TileRows tr(u.pm);
;         float* xb = tr.tb == 0 ? xc + (size_t)tr.b * CTXL * DM : out + ((size_t)tr.b * SEQ + (tr.tb - 1) * 256) * DM;
;         const float* gate = mods_l + (size_t)(tr.tb == 0 ? 8 : tr.b) * 6144 + gi * DM;
;         if (u.batch == 0) {
;             pg8::epi_foreach(acc, wr, wc, fr, fq, [&](int rl, int cl, const f32x4& v) {
;                 const int c = u.pn * 256 + cl; float* p = xb + (size_t)rl * DM + c;
;                 const f32x4 gt = *(const f32x4*)(gate + c); f32x4 xv = *(f32x4*)p; xv += gt * v; *(f32x4*)p = xv; });
;         } else {
;             float* pb = PB + (size_t)((u.batch - 1) * 32 + u.aux) * 65536;
;             pg8::epi_foreach(acc, wr, wc, fr, fq, [&](int rl, int cl, const f32x4& v) {
;                 const f32x4 gt = *(const f32x4*)(gate + u.pn * 256 + cl); *(f32x4*)(pb + rl * 256 + cl) = gt * v; });
.LBB0_1364:
	s_add_u32 s5, s62, s24
	s_addc_u32 s9, s63, s25
	s_add_u32 s8, s5, 0x5000
	s_addc_u32 s9, s9, 0
	s_mov_b64 s[24:25], -1
	s_and_b64 vcc, exec, s[0:1]
	s_cbranch_vccz .LBB0_1367
	s_lshl_b32 s0, s64, 5
	s_add_i32 s0, s78, s0
	s_sub_i32 s0, s0, 32
	s_ashr_i32 s1, s0, 31
	s_lshl_b64 s[0:1], s[0:1], 18
	s_add_u32 s0, s42, s0
	s_addc_u32 s1, s43, s1
	s_lshl_b32 s24, s46, 8
	s_ashr_i32 s25, s24, 31
	v_lshl_add_u32 v136, v146, 2, s75
	s_lshl_b64 s[24:25], s[24:25], 2
	s_add_u32 s24, s8, s24
	v_ashrrev_i32_e32 v137, 31, v136
	s_addc_u32 s25, s9, s25
	v_lshlrev_b64 v[138:139], 2, v[136:137]
	v_lshl_add_u64 v[136:137], s[24:25], 0, v[138:139]
	v_lshl_add_u32 v140, v147, 8, s2
	v_ashrrev_i32_e32 v141, 31, v140
	v_lshl_add_u64 v[152:153], v[140:141], 2, s[0:1]
	v_lshl_add_u64 v[152:153], v[152:153], 0, v[138:139]
	global_load_dwordx4 v[148:151], v[136:137], off
	global_load_dwordx4 v[156:159], v[136:137], off offset:64
	global_load_dwordx4 v[160:163], v[136:137], off offset:512
	global_load_dwordx4 v[164:167], v[136:137], off offset:576
	s_waitcnt vmcnt(0)
	v_pk_mul_f32 v[170:171], v[128:129], v[150:151]
	v_pk_mul_f32 v[168:169], v[126:127], v[148:149]
	global_store_dwordx4 v[152:153], v[168:171], off
	v_pk_mul_f32 v[174:175], v[124:125], v[158:159]
	v_pk_mul_f32 v[172:173], v[122:123], v[156:157]
	global_store_dwordx4 v[152:153], v[172:175], off offset:64
	v_pk_mul_f32 v[178:179], v[120:121], v[162:163]
	v_pk_mul_f32 v[176:177], v[118:119], v[160:161]
	global_store_dwordx4 v[152:153], v[176:179], off offset:512
	v_pk_mul_f32 v[182:183], v[116:117], v[166:167]
	v_pk_mul_f32 v[180:181], v[114:115], v[164:165]
	global_store_dwordx4 v[152:153], v[180:183], off offset:576
	s_mov_b32 s100, 0x4000
	s_mov_b32 s101, 0
	v_lshl_add_u64 v[152:153], v[152:153], 0, s[100:101]
	v_pk_mul_f32 v[186:187], v[112:113], v[150:151]
	v_pk_mul_f32 v[184:185], v[110:111], v[148:149]
	global_store_dwordx4 v[152:153], v[184:187], off
	v_pk_mul_f32 v[190:191], v[108:109], v[158:159]
	v_pk_mul_f32 v[188:189], v[106:107], v[156:157]
	global_store_dwordx4 v[152:153], v[188:191], off offset:64
	v_pk_mul_f32 v[194:195], v[104:105], v[162:163]
	v_pk_mul_f32 v[192:193], v[102:103], v[160:161]
	global_store_dwordx4 v[152:153], v[192:195], off offset:512
	v_pk_mul_f32 v[198:199], v[100:101], v[166:167]
	v_pk_mul_f32 v[196:197], v[98:99], v[164:165]
	global_store_dwordx4 v[152:153], v[196:199], off offset:576
	v_lshl_add_u64 v[152:153], v[152:153], 0, s[100:101]
	v_pk_mul_f32 v[170:171], v[96:97], v[150:151]
	v_pk_mul_f32 v[168:169], v[94:95], v[148:149]
	global_store_dwordx4 v[152:153], v[168:171], off
	v_pk_mul_f32 v[174:175], v[92:93], v[158:159]
	v_pk_mul_f32 v[172:173], v[90:91], v[156:157]
	global_store_dwordx4 v[152:153], v[172:175], off offset:64
	v_pk_mul_f32 v[178:179], v[88:89], v[162:163]
	v_pk_mul_f32 v[176:177], v[86:87], v[160:161]
	global_store_dwordx4 v[152:153], v[176:179], off offset:512
	v_pk_mul_f32 v[182:183], v[84:85], v[166:167]
	v_pk_mul_f32 v[180:181], v[82:83], v[164:165]
	global_store_dwordx4 v[152:153], v[180:183], off offset:576
	v_lshl_add_u64 v[152:153], v[152:153], 0, s[100:101]
	v_pk_mul_f32 v[186:187], v[80:81], v[150:151]
	v_pk_mul_f32 v[184:185], v[78:79], v[148:149]
	global_store_dwordx4 v[152:153], v[184:187], off
	v_pk_mul_f32 v[190:191], v[76:77], v[158:159]
	v_pk_mul_f32 v[188:189], v[74:75], v[156:157]
	global_store_dwordx4 v[152:153], v[188:191], off offset:64
	v_pk_mul_f32 v[194:195], v[72:73], v[162:163]
	v_pk_mul_f32 v[192:193], v[70:71], v[160:161]
	global_store_dwordx4 v[152:153], v[192:195], off offset:512
	v_pk_mul_f32 v[198:199], v[68:69], v[166:167]
	v_pk_mul_f32 v[196:197], v[66:67], v[164:165]
	global_store_dwordx4 v[152:153], v[196:199], off offset:576
	s_mov_b32 s100, 0x14000
	v_lshl_add_u64 v[152:153], v[152:153], 0, s[100:101]
	v_pk_mul_f32 v[170:171], v[64:65], v[150:151]
	v_pk_mul_f32 v[168:169], v[62:63], v[148:149]
	global_store_dwordx4 v[152:153], v[168:171], off
	v_pk_mul_f32 v[174:175], v[60:61], v[158:159]
	v_pk_mul_f32 v[172:173], v[58:59], v[156:157]
	global_store_dwordx4 v[152:153], v[172:175], off offset:64
	v_pk_mul_f32 v[178:179], v[56:57], v[162:163]
	v_pk_mul_f32 v[176:177], v[54:55], v[160:161]
	global_store_dwordx4 v[152:153], v[176:179], off offset:512
	v_pk_mul_f32 v[182:183], v[52:53], v[166:167]
	v_pk_mul_f32 v[180:181], v[50:51], v[164:165]
	global_store_dwordx4 v[152:153], v[180:183], off offset:576
	s_mov_b32 s100, 0x4000
	v_lshl_add_u64 v[152:153], v[152:153], 0, s[100:101]
	v_pk_mul_f32 v[186:187], v[48:49], v[150:151]
	v_pk_mul_f32 v[184:185], v[46:47], v[148:149]
	global_store_dwordx4 v[152:153], v[184:187], off
	v_pk_mul_f32 v[190:191], v[44:45], v[158:159]
	v_pk_mul_f32 v[188:189], v[42:43], v[156:157]
	global_store_dwordx4 v[152:153], v[188:191], off offset:64
	v_pk_mul_f32 v[194:195], v[40:41], v[162:163]
	v_pk_mul_f32 v[192:193], v[38:39], v[160:161]
	global_store_dwordx4 v[152:153], v[192:195], off offset:512
	v_pk_mul_f32 v[198:199], v[36:37], v[166:167]
	v_pk_mul_f32 v[196:197], v[34:35], v[164:165]
	global_store_dwordx4 v[152:153], v[196:199], off offset:576
	v_lshl_add_u64 v[152:153], v[152:153], 0, s[100:101]
	v_pk_mul_f32 v[170:171], v[32:33], v[150:151]
	v_pk_mul_f32 v[168:169], v[30:31], v[148:149]
	global_store_dwordx4 v[152:153], v[168:171], off
	v_pk_mul_f32 v[174:175], v[28:29], v[158:159]
	v_pk_mul_f32 v[172:173], v[26:27], v[156:157]
	global_store_dwordx4 v[152:153], v[172:175], off offset:64
	v_pk_mul_f32 v[178:179], v[24:25], v[162:163]
	v_pk_mul_f32 v[176:177], v[22:23], v[160:161]
	global_store_dwordx4 v[152:153], v[176:179], off offset:512
	v_pk_mul_f32 v[182:183], v[20:21], v[166:167]
	v_pk_mul_f32 v[180:181], v[18:19], v[164:165]
	global_store_dwordx4 v[152:153], v[180:183], off offset:576
	v_lshl_add_u64 v[152:153], v[152:153], 0, s[100:101]
	v_pk_mul_f32 v[186:187], v[16:17], v[150:151]
	v_pk_mul_f32 v[184:185], v[14:15], v[148:149]
	global_store_dwordx4 v[152:153], v[184:187], off
	v_pk_mul_f32 v[190:191], v[12:13], v[158:159]
	v_pk_mul_f32 v[188:189], v[10:11], v[156:157]
	global_store_dwordx4 v[152:153], v[188:191], off offset:64
	v_pk_mul_f32 v[194:195], v[8:9], v[162:163]
	v_pk_mul_f32 v[192:193], v[6:7], v[160:161]
	global_store_dwordx4 v[152:153], v[192:195], off offset:512
	v_pk_mul_f32 v[198:199], v[4:5], v[166:167]
	v_pk_mul_f32 v[196:197], v[2:3], v[164:165]
	global_store_dwordx4 v[152:153], v[196:199], off offset:576
	s_cbranch_execz .LBB0_1368

;     __device__ __forceinline__ void operator()(const f32x4 (&acc)[2][2][4][2], const Unit& u, int wr, int wc, int fr, int fq) const {
;         const TileRows tr(u.pm);
;         float* xb = tr.tb == 0 ? xc + (size_t)tr.b * CTXL * DM : out + ((size_t)tr.b * SEQ + (tr.tb - 1) * 256) * DM;
;         const float* gate = mods_l + (size_t)(tr.tb == 0 ? 8 : tr.b) * 6144 + gi * DM;
;         if (u.batch == 0) {
;             pg8::epi_foreach(acc, wr, wc, fr, fq, [&](int rl, int cl, const f32x4& v) {
;                 const int c = u.pn * 256 + cl; float* p = xb + (size_t)rl * DM + c;
;                 const f32x4 gt = *(const f32x4*)(gate + c); f32x4 xv = *(f32x4*)p; xv += gt * v; *(f32x4*)p = xv; });
.LBB0_1368:
	s_lshl_b32 s0, s46, 8
	v_add_u32_e32 v136, s74, v147
	s_or_b32 s0, s0, s75
	v_ashrrev_i32_e32 v137, 31, v136
	v_lshl_add_u32 v154, v146, 2, s0
	v_lshlrev_b64 v[138:139], 12, v[136:137]
	v_ashrrev_i32_e32 v155, 31, v154
	v_lshl_add_u64 v[138:139], s[48:49], 0, v[138:139]
	v_lshlrev_b64 v[140:141], 2, v[154:155]
	v_lshl_add_u64 v[156:157], v[138:139], 0, v[140:141]
	v_lshl_add_u64 v[138:139], s[8:9], 0, v[140:141]
	global_load_dwordx4 v[148:151], v[138:139], off
	global_load_dwordx4 v[152:155], v[138:139], off offset:64
	global_load_dwordx4 v[160:163], v[138:139], off offset:512
	global_load_dwordx4 v[164:167], v[138:139], off offset:576
	s_mov_b32 s100, 0x10000
	s_mov_b32 s101, 0
	v_lshl_add_u64 v[158:159], v[156:157], 0, s[100:101]
	v_lshl_add_u64 v[192:193], v[158:159], 0, s[100:101]
	v_lshl_add_u64 v[194:195], v[192:193], 0, s[100:101]
	s_mov_b32 s100, 0x50000
	v_lshl_add_u64 v[196:197], v[194:195], 0, s[100:101]
	s_mov_b32 s100, 0x10000
	v_lshl_add_u64 v[198:199], v[196:197], 0, s[100:101]
	v_lshl_add_u64 v[200:201], v[198:199], 0, s[100:101]
	v_lshl_add_u64 v[202:203], v[200:201], 0, s[100:101]
	global_load_dwordx4 v[168:171], v[156:157], off
	global_load_dwordx4 v[172:175], v[156:157], off offset:64
	global_load_dwordx4 v[176:179], v[156:157], off offset:512
	global_load_dwordx4 v[180:183], v[156:157], off offset:576
	global_load_dwordx4 v[184:187], v[158:159], off
	global_load_dwordx4 v[188:191], v[158:159], off offset:64
	global_load_dwordx4 v[136:139], v[158:159], off offset:512
	s_waitcnt vmcnt(6)
	v_pk_fma_f32 v[128:129], v[128:129], v[150:151], v[170:171]
	v_pk_fma_f32 v[126:127], v[126:127], v[148:149], v[168:169]
	global_store_dwordx4 v[156:157], v[126:129], off
	global_load_dwordx4 v[168:171], v[158:159], off offset:576
	s_waitcnt vmcnt(7)
	v_pk_fma_f32 v[124:125], v[124:125], v[154:155], v[174:175]
	v_pk_fma_f32 v[122:123], v[122:123], v[152:153], v[172:173]
	global_store_dwordx4 v[156:157], v[122:125], off offset:64
	global_load_dwordx4 v[172:175], v[192:193], off
	s_waitcnt vmcnt(8)
	v_pk_fma_f32 v[120:121], v[120:121], v[162:163], v[178:179]
	v_pk_fma_f32 v[118:119], v[118:119], v[160:161], v[176:177]
	global_store_dwordx4 v[156:157], v[118:121], off offset:512
	global_load_dwordx4 v[176:179], v[192:193], off offset:64
	s_waitcnt vmcnt(9)
	v_pk_fma_f32 v[116:117], v[116:117], v[166:167], v[182:183]
	v_pk_fma_f32 v[114:115], v[114:115], v[164:165], v[180:181]
	global_store_dwordx4 v[156:157], v[114:117], off offset:576
	global_load_dwordx4 v[180:183], v[192:193], off offset:512
	s_waitcnt vmcnt(10)
	v_pk_fma_f32 v[112:113], v[112:113], v[150:151], v[186:187]
	v_pk_fma_f32 v[110:111], v[110:111], v[148:149], v[184:185]
	global_store_dwordx4 v[158:159], v[110:113], off
	global_load_dwordx4 v[184:187], v[192:193], off offset:576
	s_waitcnt vmcnt(11)
	v_pk_fma_f32 v[108:109], v[108:109], v[154:155], v[190:191]
	v_pk_fma_f32 v[106:107], v[106:107], v[152:153], v[188:189]
	global_store_dwordx4 v[158:159], v[106:109], off offset:64
	global_load_dwordx4 v[188:191], v[194:195], off
	s_waitcnt vmcnt(12)
	v_pk_fma_f32 v[104:105], v[104:105], v[162:163], v[138:139]
	v_pk_fma_f32 v[102:103], v[102:103], v[160:161], v[136:137]
	global_store_dwordx4 v[158:159], v[102:105], off offset:512
	global_load_dwordx4 v[136:139], v[194:195], off offset:64
	s_waitcnt vmcnt(12)
	v_pk_fma_f32 v[100:101], v[100:101], v[166:167], v[170:171]
	v_pk_fma_f32 v[98:99], v[98:99], v[164:165], v[168:169]
	global_store_dwordx4 v[158:159], v[98:101], off offset:576
	global_load_dwordx4 v[168:171], v[194:195], off offset:512
	s_waitcnt vmcnt(12)
	v_pk_fma_f32 v[96:97], v[96:97], v[150:151], v[174:175]
	v_pk_fma_f32 v[94:95], v[94:95], v[148:149], v[172:173]
	global_store_dwordx4 v[192:193], v[94:97], off
	global_load_dwordx4 v[172:175], v[194:195], off offset:576
	s_waitcnt vmcnt(12)
	v_pk_fma_f32 v[92:93], v[92:93], v[154:155], v[178:179]
	v_pk_fma_f32 v[90:91], v[90:91], v[152:153], v[176:177]
	global_store_dwordx4 v[192:193], v[90:93], off offset:64
	global_load_dwordx4 v[176:179], v[196:197], off
	s_waitcnt vmcnt(12)
	v_pk_fma_f32 v[88:89], v[88:89], v[162:163], v[182:183]
	v_pk_fma_f32 v[86:87], v[86:87], v[160:161], v[180:181]
	global_store_dwordx4 v[192:193], v[86:89], off offset:512
	global_load_dwordx4 v[180:183], v[196:197], off offset:64
	s_waitcnt vmcnt(12)
	v_pk_fma_f32 v[84:85], v[84:85], v[166:167], v[186:187]
	v_pk_fma_f32 v[82:83], v[82:83], v[164:165], v[184:185]
	global_store_dwordx4 v[192:193], v[82:85], off offset:576
	global_load_dwordx4 v[184:187], v[196:197], off offset:512
	s_waitcnt vmcnt(12)
;     __device__ __forceinline__ void operator()(const f32x4 (&acc)[2][2][4][2], const Unit& u, int wr, int wc, int fr, int fq) const {
;     ...
;         if (u.batch == 0) {
;             pg8::epi_foreach(acc, wr, wc, fr, fq, [&](int rl, int cl, const f32x4& v) {
;                 const int c = u.pn * 256 + cl; float* p = xb + (size_t)rl * DM + c;
;                 const f32x4 gt = *(const f32x4*)(gate + c); f32x4 xv = *(f32x4*)p; xv += gt * v; *(f32x4*)p = xv; });
	v_pk_fma_f32 v[80:81], v[80:81], v[150:151], v[190:191]
	v_pk_fma_f32 v[78:79], v[78:79], v[148:149], v[188:189]
	global_store_dwordx4 v[194:195], v[78:81], off
	global_load_dwordx4 v[188:191], v[196:197], off offset:576
	s_waitcnt vmcnt(12)
	v_pk_fma_f32 v[76:77], v[76:77], v[154:155], v[138:139]
	v_pk_fma_f32 v[74:75], v[74:75], v[152:153], v[136:137]
	global_store_dwordx4 v[194:195], v[74:77], off offset:64
	global_load_dwordx4 v[136:139], v[198:199], off
	s_waitcnt vmcnt(12)
	v_pk_fma_f32 v[72:73], v[72:73], v[162:163], v[170:171]
	v_pk_fma_f32 v[70:71], v[70:71], v[160:161], v[168:169]
	global_store_dwordx4 v[194:195], v[70:73], off offset:512
	global_load_dwordx4 v[168:171], v[198:199], off offset:64
	s_waitcnt vmcnt(12)
	v_pk_fma_f32 v[68:69], v[68:69], v[166:167], v[174:175]
	v_pk_fma_f32 v[66:67], v[66:67], v[164:165], v[172:173]
	global_store_dwordx4 v[194:195], v[66:69], off offset:576
	global_load_dwordx4 v[172:175], v[198:199], off offset:512
	s_waitcnt vmcnt(12)
	v_pk_fma_f32 v[64:65], v[64:65], v[150:151], v[178:179]
	v_pk_fma_f32 v[62:63], v[62:63], v[148:149], v[176:177]
	global_store_dwordx4 v[196:197], v[62:65], off
	global_load_dwordx4 v[176:179], v[198:199], off offset:576
	s_waitcnt vmcnt(12)
	v_pk_fma_f32 v[60:61], v[60:61], v[154:155], v[182:183]
	v_pk_fma_f32 v[58:59], v[58:59], v[152:153], v[180:181]
	global_store_dwordx4 v[196:197], v[58:61], off offset:64
	global_load_dwordx4 v[180:183], v[200:201], off
	s_waitcnt vmcnt(12)
	v_pk_fma_f32 v[56:57], v[56:57], v[162:163], v[186:187]
	v_pk_fma_f32 v[54:55], v[54:55], v[160:161], v[184:185]
	global_store_dwordx4 v[196:197], v[54:57], off offset:512
	global_load_dwordx4 v[184:187], v[200:201], off offset:64
	s_waitcnt vmcnt(12)
	v_pk_fma_f32 v[52:53], v[52:53], v[166:167], v[190:191]
	v_pk_fma_f32 v[50:51], v[50:51], v[164:165], v[188:189]
	global_store_dwordx4 v[196:197], v[50:53], off offset:576
	global_load_dwordx4 v[188:191], v[200:201], off offset:512
	s_waitcnt vmcnt(12)
	v_pk_fma_f32 v[48:49], v[48:49], v[150:151], v[138:139]
	v_pk_fma_f32 v[46:47], v[46:47], v[148:149], v[136:137]
	global_store_dwordx4 v[198:199], v[46:49], off
	global_load_dwordx4 v[136:139], v[200:201], off offset:576
	s_waitcnt vmcnt(12)
	v_pk_fma_f32 v[44:45], v[44:45], v[154:155], v[170:171]
	v_pk_fma_f32 v[42:43], v[42:43], v[152:153], v[168:169]
	global_store_dwordx4 v[198:199], v[42:45], off offset:64
	global_load_dwordx4 v[168:171], v[202:203], off
	s_waitcnt vmcnt(12)
	v_pk_fma_f32 v[40:41], v[40:41], v[162:163], v[174:175]
	v_pk_fma_f32 v[38:39], v[38:39], v[160:161], v[172:173]
	global_store_dwordx4 v[198:199], v[38:41], off offset:512
	global_load_dwordx4 v[172:175], v[202:203], off offset:64
	s_waitcnt vmcnt(12)
	v_pk_fma_f32 v[36:37], v[36:37], v[166:167], v[178:179]
	v_pk_fma_f32 v[34:35], v[34:35], v[164:165], v[176:177]
	global_store_dwordx4 v[198:199], v[34:37], off offset:576
	global_load_dwordx4 v[176:179], v[202:203], off offset:512
	s_waitcnt vmcnt(12)
	v_pk_fma_f32 v[32:33], v[32:33], v[150:151], v[182:183]
	v_pk_fma_f32 v[30:31], v[30:31], v[148:149], v[180:181]
	global_store_dwordx4 v[200:201], v[30:33], off
	global_load_dwordx4 v[180:183], v[202:203], off offset:576
	s_waitcnt vmcnt(12)
	v_pk_fma_f32 v[28:29], v[28:29], v[154:155], v[186:187]
	v_pk_fma_f32 v[26:27], v[26:27], v[152:153], v[184:185]
	global_store_dwordx4 v[200:201], v[26:29], off offset:64
	s_waitcnt vmcnt(11)
	v_pk_fma_f32 v[24:25], v[24:25], v[162:163], v[190:191]
	v_pk_fma_f32 v[22:23], v[22:23], v[160:161], v[188:189]
	global_store_dwordx4 v[200:201], v[22:25], off offset:512
	s_waitcnt vmcnt(10)
	v_pk_fma_f32 v[20:21], v[20:21], v[166:167], v[138:139]
	v_pk_fma_f32 v[18:19], v[18:19], v[164:165], v[136:137]
	global_store_dwordx4 v[200:201], v[18:21], off offset:576
	s_waitcnt vmcnt(9)
	v_pk_fma_f32 v[16:17], v[16:17], v[150:151], v[170:171]
	v_pk_fma_f32 v[14:15], v[14:15], v[148:149], v[168:169]
	global_store_dwordx4 v[202:203], v[14:17], off
	s_waitcnt vmcnt(8)
	v_pk_fma_f32 v[12:13], v[12:13], v[154:155], v[174:175]
	v_pk_fma_f32 v[10:11], v[10:11], v[152:153], v[172:173]
	global_store_dwordx4 v[202:203], v[10:13], off offset:64
	s_waitcnt vmcnt(7)
	v_pk_fma_f32 v[8:9], v[8:9], v[162:163], v[178:179]
	v_pk_fma_f32 v[6:7], v[6:7], v[160:161], v[176:177]
	global_store_dwordx4 v[202:203], v[6:9], off offset:512
	s_waitcnt vmcnt(6)
	v_pk_fma_f32 v[4:5], v[4:5], v[166:167], v[182:183]
	v_pk_fma_f32 v[2:3], v[2:3], v[164:165], v[180:181]
	global_store_dwordx4 v[202:203], v[2:5], off offset:576
	s_and_b64 vcc, exec, s[40:41]
	s_mov_b64 s[0:1], -1
	s_cbranch_vccnz .LBB0_1341

;     __device__ __forceinline__ void operator()(const f32x4 (&acc)[2][2][4][2], const Unit& u, int wr, int wc, int fr, int fq) const {
;         const TileRows tr(u.pm);
;         float* xb = tr.tb == 0 ? xc + (size_t)tr.b * CTXL * DM : out + ((size_t)tr.b * SEQ + (tr.tb - 1) * 256) * DM;
;         const float* gate = mods_l + (size_t)(tr.tb == 0 ? 8 : tr.b) * 6144 + gi * DM;
;         if (u.batch == 0) {
;             pg8::epi_foreach(acc, wr, wc, fr, fq, [&](int rl, int cl, const f32x4& v) {
;                 const int c = u.pn * 256 + cl; float* p = xb + (size_t)rl * DM + c;
;                 const f32x4 gt = *(const f32x4*)(gate + c); f32x4 xv = *(f32x4*)p; xv += gt * v; *(f32x4*)p = xv; });
;         } else {
;             float* pb = PB + (size_t)((u.batch - 1) * 32 + u.aux) * 65536;
;             pg8::epi_foreach(acc, wr, wc, fr, fq, [&](int rl, int cl, const f32x4& v) {
;                 const f32x4 gt = *(const f32x4*)(gate + u.pn * 256 + cl); *(f32x4*)(pb + rl * 256 + cl) = gt * v; });
.LBB0_1401:
	s_add_u32 s0, s62, s24
	s_addc_u32 s1, s63, s25
	s_add_u32 s0, s0, 0x5000
	s_addc_u32 s1, s1, 0
	s_lshl_b32 s8, s8, 8
	s_cmp_lg_u32 s9, 0
	v_lshl_add_u32 v132, v132, 2, s56
	s_cbranch_scc0 .LBB0_1408
	s_ashr_i32 s9, s8, 31
	s_lshl_b64 s[24:25], s[8:9], 2
	s_add_u32 s24, s0, s24
	v_ashrrev_i32_e32 v133, 31, v132
	s_addc_u32 s25, s1, s25
	v_lshlrev_b64 v[136:137], 2, v[132:133]
	v_lshl_add_u64 v[134:135], s[24:25], 0, v[136:137]
	v_lshl_add_u32 v138, v144, 8, s70
	v_ashrrev_i32_e32 v139, 31, v138
	v_lshl_add_u64 v[150:151], v[138:139], 2, s[42:43]
	v_lshl_add_u64 v[150:151], v[150:151], 0, v[136:137]
	global_load_dwordx4 v[152:155], v[134:135], off
	global_load_dwordx4 v[156:159], v[134:135], off offset:64
	global_load_dwordx4 v[160:163], v[134:135], off offset:512
	global_load_dwordx4 v[164:167], v[134:135], off offset:576
	s_waitcnt vmcnt(0)
	v_pk_mul_f32 v[170:171], v[128:129], v[154:155]
	v_pk_mul_f32 v[168:169], v[126:127], v[152:153]
	global_store_dwordx4 v[150:151], v[168:171], off
	v_pk_mul_f32 v[174:175], v[124:125], v[158:159]
	v_pk_mul_f32 v[172:173], v[122:123], v[156:157]
	global_store_dwordx4 v[150:151], v[172:175], off offset:64
	v_pk_mul_f32 v[178:179], v[120:121], v[162:163]
	v_pk_mul_f32 v[176:177], v[118:119], v[160:161]
	global_store_dwordx4 v[150:151], v[176:179], off offset:512
	v_pk_mul_f32 v[182:183], v[116:117], v[166:167]
	v_pk_mul_f32 v[180:181], v[114:115], v[164:165]
	global_store_dwordx4 v[150:151], v[180:183], off offset:576
	s_mov_b32 s100, 0x4000
	s_mov_b32 s101, 0
	v_lshl_add_u64 v[150:151], v[150:151], 0, s[100:101]
	v_pk_mul_f32 v[186:187], v[112:113], v[154:155]
	v_pk_mul_f32 v[184:185], v[110:111], v[152:153]
	global_store_dwordx4 v[150:151], v[184:187], off
	v_pk_mul_f32 v[190:191], v[108:109], v[158:159]
	v_pk_mul_f32 v[188:189], v[106:107], v[156:157]
	global_store_dwordx4 v[150:151], v[188:191], off offset:64
	v_pk_mul_f32 v[194:195], v[104:105], v[162:163]
	v_pk_mul_f32 v[192:193], v[102:103], v[160:161]
	global_store_dwordx4 v[150:151], v[192:195], off offset:512
	v_pk_mul_f32 v[198:199], v[100:101], v[166:167]
	v_pk_mul_f32 v[196:197], v[98:99], v[164:165]
	global_store_dwordx4 v[150:151], v[196:199], off offset:576
	v_lshl_add_u64 v[150:151], v[150:151], 0, s[100:101]
	v_pk_mul_f32 v[170:171], v[96:97], v[154:155]
	v_pk_mul_f32 v[168:169], v[94:95], v[152:153]
	global_store_dwordx4 v[150:151], v[168:171], off
	v_pk_mul_f32 v[174:175], v[92:93], v[158:159]
	v_pk_mul_f32 v[172:173], v[90:91], v[156:157]
	global_store_dwordx4 v[150:151], v[172:175], off offset:64
	v_pk_mul_f32 v[178:179], v[88:89], v[162:163]
	v_pk_mul_f32 v[176:177], v[86:87], v[160:161]
	global_store_dwordx4 v[150:151], v[176:179], off offset:512
	v_pk_mul_f32 v[182:183], v[84:85], v[166:167]
	v_pk_mul_f32 v[180:181], v[82:83], v[164:165]
	global_store_dwordx4 v[150:151], v[180:183], off offset:576
	v_lshl_add_u64 v[150:151], v[150:151], 0, s[100:101]
	v_pk_mul_f32 v[186:187], v[80:81], v[154:155]
	v_pk_mul_f32 v[184:185], v[78:79], v[152:153]
	global_store_dwordx4 v[150:151], v[184:187], off
	v_pk_mul_f32 v[190:191], v[76:77], v[158:159]
	v_pk_mul_f32 v[188:189], v[74:75], v[156:157]
	global_store_dwordx4 v[150:151], v[188:191], off offset:64
	v_pk_mul_f32 v[194:195], v[72:73], v[162:163]
	v_pk_mul_f32 v[192:193], v[70:71], v[160:161]
	global_store_dwordx4 v[150:151], v[192:195], off offset:512
	v_pk_mul_f32 v[198:199], v[68:69], v[166:167]
	v_pk_mul_f32 v[196:197], v[66:67], v[164:165]
	global_store_dwordx4 v[150:151], v[196:199], off offset:576
	s_mov_b32 s100, 0x14000
	v_lshl_add_u64 v[150:151], v[150:151], 0, s[100:101]
	v_pk_mul_f32 v[170:171], v[64:65], v[154:155]
	v_pk_mul_f32 v[168:169], v[62:63], v[152:153]
	global_store_dwordx4 v[150:151], v[168:171], off
	v_pk_mul_f32 v[174:175], v[60:61], v[158:159]
	v_pk_mul_f32 v[172:173], v[58:59], v[156:157]
	global_store_dwordx4 v[150:151], v[172:175], off offset:64
	v_pk_mul_f32 v[178:179], v[56:57], v[162:163]
	v_pk_mul_f32 v[176:177], v[54:55], v[160:161]
	global_store_dwordx4 v[150:151], v[176:179], off offset:512
	v_pk_mul_f32 v[182:183], v[52:53], v[166:167]
	v_pk_mul_f32 v[180:181], v[50:51], v[164:165]
	global_store_dwordx4 v[150:151], v[180:183], off offset:576
	s_mov_b32 s100, 0x4000
	v_lshl_add_u64 v[150:151], v[150:151], 0, s[100:101]
	v_pk_mul_f32 v[186:187], v[48:49], v[154:155]
	v_pk_mul_f32 v[184:185], v[46:47], v[152:153]
	global_store_dwordx4 v[150:151], v[184:187], off
	v_pk_mul_f32 v[190:191], v[44:45], v[158:159]
	v_pk_mul_f32 v[188:189], v[42:43], v[156:157]
	global_store_dwordx4 v[150:151], v[188:191], off offset:64
	v_pk_mul_f32 v[194:195], v[40:41], v[162:163]
	v_pk_mul_f32 v[192:193], v[38:39], v[160:161]
	global_store_dwordx4 v[150:151], v[192:195], off offset:512
	v_pk_mul_f32 v[198:199], v[36:37], v[166:167]
	v_pk_mul_f32 v[196:197], v[34:35], v[164:165]
	global_store_dwordx4 v[150:151], v[196:199], off offset:576
	v_lshl_add_u64 v[150:151], v[150:151], 0, s[100:101]
	v_pk_mul_f32 v[170:171], v[32:33], v[154:155]
	v_pk_mul_f32 v[168:169], v[30:31], v[152:153]
	global_store_dwordx4 v[150:151], v[168:171], off
	v_pk_mul_f32 v[174:175], v[28:29], v[158:159]
	v_pk_mul_f32 v[172:173], v[26:27], v[156:157]
	global_store_dwordx4 v[150:151], v[172:175], off offset:64
	v_pk_mul_f32 v[178:179], v[24:25], v[162:163]
	v_pk_mul_f32 v[176:177], v[22:23], v[160:161]
	global_store_dwordx4 v[150:151], v[176:179], off offset:512
	v_pk_mul_f32 v[182:183], v[20:21], v[166:167]
	v_pk_mul_f32 v[180:181], v[18:19], v[164:165]
	global_store_dwordx4 v[150:151], v[180:183], off offset:576
	v_lshl_add_u64 v[150:151], v[150:151], 0, s[100:101]
	v_pk_mul_f32 v[186:187], v[16:17], v[154:155]
	v_pk_mul_f32 v[184:185], v[14:15], v[152:153]
	global_store_dwordx4 v[150:151], v[184:187], off
	v_pk_mul_f32 v[190:191], v[12:13], v[158:159]
	v_pk_mul_f32 v[188:189], v[10:11], v[156:157]
	global_store_dwordx4 v[150:151], v[188:191], off offset:64
	v_pk_mul_f32 v[194:195], v[8:9], v[162:163]
	v_pk_mul_f32 v[192:193], v[6:7], v[160:161]
	global_store_dwordx4 v[150:151], v[192:195], off offset:512
	v_pk_mul_f32 v[198:199], v[4:5], v[166:167]
	v_pk_mul_f32 v[196:197], v[2:3], v[164:165]
	global_store_dwordx4 v[150:151], v[196:199], off offset:576
	s_cbranch_execnz .LBB0_1404
;     __device__ __forceinline__ void operator()(const f32x4 (&acc)[2][2][4][2], const Unit& u, int wr, int wc, int fr, int fq) const {
;         const TileRows tr(u.pm);
;         float* xb = tr.tb == 0 ? xc + (size_t)tr.b * CTXL * DM : out + ((size_t)tr.b * SEQ + (tr.tb - 1) * 256) * DM;
;         const float* gate = mods_l + (size_t)(tr.tb == 0 ? 8 : tr.b) * 6144 + gi * DM;
;         if (u.batch == 0) {
;             pg8::epi_foreach(acc, wr, wc, fr, fq, [&](int rl, int cl, const f32x4& v) {
;                 const int c = u.pn * 256 + cl; float* p = xb + (size_t)rl * DM + c;
;                 const f32x4 gt = *(const f32x4*)(gate + c); f32x4 xv = *(f32x4*)p; xv += gt * v; *(f32x4*)p = xv; });
.LBB0_1403:
	s_nop 0
	v_add_u32_e32 v134, s33, v144
	v_ashrrev_i32_e32 v135, 31, v134
	v_add_u32_e32 v138, s8, v132
	v_lshlrev_b64 v[136:137], 12, v[134:135]
	v_ashrrev_i32_e32 v139, 31, v138
	v_lshl_add_u64 v[132:133], s[44:45], 0, v[136:137]
	v_lshlrev_b64 v[136:137], 2, v[138:139]
	v_lshl_add_u64 v[152:153], v[132:133], 0, v[136:137]
	v_lshl_add_u64 v[132:133], s[0:1], 0, v[136:137]
	global_load_dwordx4 v[136:139], v[132:133], off
	global_load_dwordx4 v[144:147], v[132:133], off offset:64
	global_load_dwordx4 v[148:151], v[132:133], off offset:512
	global_load_dwordx4 v[156:159], v[132:133], off offset:576
	s_mov_b32 s100, 0x10000
	s_mov_b32 s101, 0
	v_lshl_add_u64 v[154:155], v[152:153], 0, s[100:101]
	v_lshl_add_u64 v[188:189], v[154:155], 0, s[100:101]
	v_lshl_add_u64 v[190:191], v[188:189], 0, s[100:101]
	s_mov_b32 s100, 0x50000
	v_lshl_add_u64 v[192:193], v[190:191], 0, s[100:101]
	s_mov_b32 s100, 0x10000
	v_lshl_add_u64 v[194:195], v[192:193], 0, s[100:101]
	v_lshl_add_u64 v[196:197], v[194:195], 0, s[100:101]
	v_lshl_add_u64 v[198:199], v[196:197], 0, s[100:101]
	global_load_dwordx4 v[160:163], v[152:153], off
	global_load_dwordx4 v[164:167], v[152:153], off offset:64
	global_load_dwordx4 v[168:171], v[152:153], off offset:512
	global_load_dwordx4 v[172:175], v[152:153], off offset:576
	global_load_dwordx4 v[176:179], v[154:155], off
	global_load_dwordx4 v[180:183], v[154:155], off offset:64
	global_load_dwordx4 v[184:187], v[154:155], off offset:512
	global_load_dwordx4 v[132:135], v[154:155], off offset:576
	s_waitcnt vmcnt(7)
	v_pk_fma_f32 v[128:129], v[128:129], v[138:139], v[162:163]
	v_pk_fma_f32 v[126:127], v[126:127], v[136:137], v[160:161]
	global_store_dwordx4 v[152:153], v[126:129], off
	global_load_dwordx4 v[160:163], v[188:189], off
	s_waitcnt vmcnt(8)
	v_pk_fma_f32 v[124:125], v[124:125], v[146:147], v[166:167]
	v_pk_fma_f32 v[122:123], v[122:123], v[144:145], v[164:165]
	global_store_dwordx4 v[152:153], v[122:125], off offset:64
	global_load_dwordx4 v[164:167], v[188:189], off offset:64
	s_waitcnt vmcnt(9)
	v_pk_fma_f32 v[120:121], v[120:121], v[150:151], v[170:171]
	v_pk_fma_f32 v[118:119], v[118:119], v[148:149], v[168:169]
	global_store_dwordx4 v[152:153], v[118:121], off offset:512
	global_load_dwordx4 v[168:171], v[188:189], off offset:512
	s_waitcnt vmcnt(10)
	v_pk_fma_f32 v[116:117], v[116:117], v[158:159], v[174:175]
	v_pk_fma_f32 v[114:115], v[114:115], v[156:157], v[172:173]
	global_store_dwordx4 v[152:153], v[114:117], off offset:576
	global_load_dwordx4 v[172:175], v[188:189], off offset:576
	s_waitcnt vmcnt(11)
	v_pk_fma_f32 v[112:113], v[112:113], v[138:139], v[178:179]
	v_pk_fma_f32 v[110:111], v[110:111], v[136:137], v[176:177]
	global_store_dwordx4 v[154:155], v[110:113], off
	global_load_dwordx4 v[176:179], v[190:191], off
	s_waitcnt vmcnt(12)
	v_pk_fma_f32 v[108:109], v[108:109], v[146:147], v[182:183]
	v_pk_fma_f32 v[106:107], v[106:107], v[144:145], v[180:181]
	global_store_dwordx4 v[154:155], v[106:109], off offset:64
	global_load_dwordx4 v[180:183], v[190:191], off offset:64
	s_waitcnt vmcnt(13)
	v_pk_fma_f32 v[104:105], v[104:105], v[150:151], v[186:187]
	v_pk_fma_f32 v[102:103], v[102:103], v[148:149], v[184:185]
	global_store_dwordx4 v[154:155], v[102:105], off offset:512
	global_load_dwordx4 v[184:187], v[190:191], off offset:512
	s_waitcnt vmcnt(14)
	v_pk_fma_f32 v[100:101], v[100:101], v[158:159], v[134:135]
	v_pk_fma_f32 v[98:99], v[98:99], v[156:157], v[132:133]
	global_store_dwordx4 v[154:155], v[98:101], off offset:576
	global_load_dwordx4 v[132:135], v[190:191], off offset:576
	s_waitcnt vmcnt(14)
	v_pk_fma_f32 v[96:97], v[96:97], v[138:139], v[162:163]
	v_pk_fma_f32 v[94:95], v[94:95], v[136:137], v[160:161]
	global_store_dwordx4 v[188:189], v[94:97], off
	global_load_dwordx4 v[160:163], v[192:193], off
	s_waitcnt vmcnt(14)
	v_pk_fma_f32 v[92:93], v[92:93], v[146:147], v[166:167]
	v_pk_fma_f32 v[90:91], v[90:91], v[144:145], v[164:165]
	global_store_dwordx4 v[188:189], v[90:93], off offset:64
	global_load_dwordx4 v[164:167], v[192:193], off offset:64
	s_waitcnt vmcnt(14)
	v_pk_fma_f32 v[88:89], v[88:89], v[150:151], v[170:171]
	v_pk_fma_f32 v[86:87], v[86:87], v[148:149], v[168:169]
	global_store_dwordx4 v[188:189], v[86:89], off offset:512
	global_load_dwordx4 v[168:171], v[192:193], off offset:512
	s_waitcnt vmcnt(14)
	v_pk_fma_f32 v[84:85], v[84:85], v[158:159], v[174:175]
	v_pk_fma_f32 v[82:83], v[82:83], v[156:157], v[172:173]
	global_store_dwordx4 v[188:189], v[82:85], off offset:576
	global_load_dwordx4 v[172:175], v[192:193], off offset:576
	s_waitcnt vmcnt(14)
;     __device__ __forceinline__ void operator()(const f32x4 (&acc)[2][2][4][2], const Unit& u, int wr, int wc, int fr, int fq) const {
;     ...
;         if (u.batch == 0) {
;             pg8::epi_foreach(acc, wr, wc, fr, fq, [&](int rl, int cl, const f32x4& v) {
;                 const int c = u.pn * 256 + cl; float* p = xb + (size_t)rl * DM + c;
;                 const f32x4 gt = *(const f32x4*)(gate + c); f32x4 xv = *(f32x4*)p; xv += gt * v; *(f32x4*)p = xv; });
	v_pk_fma_f32 v[80:81], v[80:81], v[138:139], v[178:179]
	v_pk_fma_f32 v[78:79], v[78:79], v[136:137], v[176:177]
	global_store_dwordx4 v[190:191], v[78:81], off
	global_load_dwordx4 v[176:179], v[194:195], off
	s_waitcnt vmcnt(14)
	v_pk_fma_f32 v[76:77], v[76:77], v[146:147], v[182:183]
	v_pk_fma_f32 v[74:75], v[74:75], v[144:145], v[180:181]
	global_store_dwordx4 v[190:191], v[74:77], off offset:64
	global_load_dwordx4 v[180:183], v[194:195], off offset:64
	s_waitcnt vmcnt(14)
	v_pk_fma_f32 v[72:73], v[72:73], v[150:151], v[186:187]
	v_pk_fma_f32 v[70:71], v[70:71], v[148:149], v[184:185]
	global_store_dwordx4 v[190:191], v[70:73], off offset:512
	global_load_dwordx4 v[184:187], v[194:195], off offset:512
	s_waitcnt vmcnt(14)
	v_pk_fma_f32 v[68:69], v[68:69], v[158:159], v[134:135]
	v_pk_fma_f32 v[66:67], v[66:67], v[156:157], v[132:133]
	global_store_dwordx4 v[190:191], v[66:69], off offset:576
	global_load_dwordx4 v[132:135], v[194:195], off offset:576
	s_waitcnt vmcnt(14)
	v_pk_fma_f32 v[64:65], v[64:65], v[138:139], v[162:163]
	v_pk_fma_f32 v[62:63], v[62:63], v[136:137], v[160:161]
	global_store_dwordx4 v[192:193], v[62:65], off
	global_load_dwordx4 v[160:163], v[196:197], off
	s_waitcnt vmcnt(14)
	v_pk_fma_f32 v[60:61], v[60:61], v[146:147], v[166:167]
	v_pk_fma_f32 v[58:59], v[58:59], v[144:145], v[164:165]
	global_store_dwordx4 v[192:193], v[58:61], off offset:64
	global_load_dwordx4 v[164:167], v[196:197], off offset:64
	s_waitcnt vmcnt(14)
	v_pk_fma_f32 v[56:57], v[56:57], v[150:151], v[170:171]
	v_pk_fma_f32 v[54:55], v[54:55], v[148:149], v[168:169]
	global_store_dwordx4 v[192:193], v[54:57], off offset:512
	global_load_dwordx4 v[168:171], v[196:197], off offset:512
	s_waitcnt vmcnt(14)
	v_pk_fma_f32 v[52:53], v[52:53], v[158:159], v[174:175]
	v_pk_fma_f32 v[50:51], v[50:51], v[156:157], v[172:173]
	global_store_dwordx4 v[192:193], v[50:53], off offset:576
	global_load_dwordx4 v[172:175], v[196:197], off offset:576
	s_waitcnt vmcnt(14)
	v_pk_fma_f32 v[48:49], v[48:49], v[138:139], v[178:179]
	v_pk_fma_f32 v[46:47], v[46:47], v[136:137], v[176:177]
	global_store_dwordx4 v[194:195], v[46:49], off
	global_load_dwordx4 v[176:179], v[198:199], off
	s_waitcnt vmcnt(14)
	v_pk_fma_f32 v[44:45], v[44:45], v[146:147], v[182:183]
	v_pk_fma_f32 v[42:43], v[42:43], v[144:145], v[180:181]
	global_store_dwordx4 v[194:195], v[42:45], off offset:64
	global_load_dwordx4 v[180:183], v[198:199], off offset:64
	s_waitcnt vmcnt(14)
	v_pk_fma_f32 v[40:41], v[40:41], v[150:151], v[186:187]
	v_pk_fma_f32 v[38:39], v[38:39], v[148:149], v[184:185]
	global_store_dwordx4 v[194:195], v[38:41], off offset:512
	global_load_dwordx4 v[184:187], v[198:199], off offset:512
	s_waitcnt vmcnt(14)
	v_pk_fma_f32 v[36:37], v[36:37], v[158:159], v[134:135]
	v_pk_fma_f32 v[34:35], v[34:35], v[156:157], v[132:133]
	global_store_dwordx4 v[194:195], v[34:37], off offset:576
	global_load_dwordx4 v[132:135], v[198:199], off offset:576
	s_waitcnt vmcnt(14)
	v_pk_fma_f32 v[32:33], v[32:33], v[138:139], v[162:163]
	v_pk_fma_f32 v[30:31], v[30:31], v[136:137], v[160:161]
	global_store_dwordx4 v[196:197], v[30:33], off
	s_waitcnt vmcnt(13)
	v_pk_fma_f32 v[28:29], v[28:29], v[146:147], v[166:167]
	v_pk_fma_f32 v[26:27], v[26:27], v[144:145], v[164:165]
	global_store_dwordx4 v[196:197], v[26:29], off offset:64
	s_waitcnt vmcnt(12)
	v_pk_fma_f32 v[24:25], v[24:25], v[150:151], v[170:171]
	v_pk_fma_f32 v[22:23], v[22:23], v[148:149], v[168:169]
	global_store_dwordx4 v[196:197], v[22:25], off offset:512
	s_waitcnt vmcnt(11)
	v_pk_fma_f32 v[20:21], v[20:21], v[158:159], v[174:175]
	v_pk_fma_f32 v[18:19], v[18:19], v[156:157], v[172:173]
	global_store_dwordx4 v[196:197], v[18:21], off offset:576
	s_waitcnt vmcnt(10)
	v_pk_fma_f32 v[16:17], v[16:17], v[138:139], v[178:179]
	v_pk_fma_f32 v[14:15], v[14:15], v[136:137], v[176:177]
	global_store_dwordx4 v[198:199], v[14:17], off
	s_waitcnt vmcnt(9)
	v_pk_fma_f32 v[12:13], v[12:13], v[146:147], v[182:183]
	v_pk_fma_f32 v[10:11], v[10:11], v[144:145], v[180:181]
	global_store_dwordx4 v[198:199], v[10:13], off offset:64
	s_waitcnt vmcnt(8)
	v_pk_fma_f32 v[8:9], v[8:9], v[150:151], v[186:187]
	v_pk_fma_f32 v[6:7], v[6:7], v[148:149], v[184:185]
	global_store_dwordx4 v[198:199], v[6:9], off offset:512
	s_waitcnt vmcnt(7)
	v_pk_fma_f32 v[4:5], v[4:5], v[158:159], v[134:135]
	v_pk_fma_f32 v[2:3], v[2:3], v[156:157], v[132:133]
	global_store_dwordx4 v[198:199], v[2:5], off offset:576

; __global__ __launch_bounds__(512, 2) void mega(Args a_) {
;     extern __shared__ __attribute__((aligned(16))) unsigned char shm[];
	.amdhsa_kernel _Z4mega4Args
		.amdhsa_group_segment_fixed_size 0
		.amdhsa_private_segment_fixed_size 0
		.amdhsa_kernarg_size 496
		.amdhsa_user_sgpr_count 2
		.amdhsa_user_sgpr_dispatch_ptr 0
		.amdhsa_user_sgpr_queue_ptr 0
		.amdhsa_user_sgpr_kernarg_segment_ptr 1
		.amdhsa_user_sgpr_dispatch_id 0
		.amdhsa_user_sgpr_kernarg_preload_length 0
		.amdhsa_user_sgpr_kernarg_preload_offset 0
		.amdhsa_user_sgpr_private_segment_size 0
		.amdhsa_uses_dynamic_stack 0
		.amdhsa_enable_private_segment 0
		.amdhsa_system_sgpr_workgroup_id_x 1
		.amdhsa_system_sgpr_workgroup_id_y 0
		.amdhsa_system_sgpr_workgroup_id_z 0
		.amdhsa_system_sgpr_workgroup_info 0
		.amdhsa_system_vgpr_workitem_id 2
		.amdhsa_next_free_vgpr 238
		.amdhsa_next_free_sgpr 102
		.amdhsa_accum_offset 240
		.amdhsa_reserve_vcc 1
		.amdhsa_float_round_mode_32 0
		.amdhsa_float_round_mode_16_64 0
		.amdhsa_float_denorm_mode_32 3
		.amdhsa_float_denorm_mode_16_64 3
		.amdhsa_dx10_clamp 1
		.amdhsa_ieee_mode 1
		.amdhsa_fp16_overflow 0
		.amdhsa_tg_split 0
		.amdhsa_exception_fp_ieee_invalid_op 0
		.amdhsa_exception_fp_denorm_src 0
		.amdhsa_exception_fp_ieee_div_zero 0
		.amdhsa_exception_fp_ieee_overflow 0
		.amdhsa_exception_fp_ieee_underflow 0
		.amdhsa_exception_fp_ieee_inexact 0
		.amdhsa_exception_int_div_zero 0
	.end_amdhsa_kernel

; #define LAS __attribute__((address_space(3)))
; __global__ __launch_bounds__(512, 2) void mega(Args a_) {
;     extern __shared__ __attribute__((aligned(16))) unsigned char shm[];
;     LAS unsigned char* lds = (LAS unsigned char*)shm;
;     cg::grid_group grid = cg::this_grid();
;     const int ph_lo = a_.ph_lo, ph_hi = a_.ph_hi;
amdhsa.kernels:
  - .agpr_count:     0
    .args:
      - .offset:         0
        .size:           240
        .value_kind:     by_value
      - .offset:         240
        .size:           4
        .value_kind:     hidden_block_count_x
      - .offset:         244
        .size:           4
        .value_kind:     hidden_block_count_y
      - .offset:         248
        .size:           4
        .value_kind:     hidden_block_count_z
      - .offset:         252
        .size:           2
        .value_kind:     hidden_group_size_x
      - .offset:         254
        .size:           2
        .value_kind:     hidden_group_size_y
      - .offset:         256
        .size:           2
        .value_kind:     hidden_group_size_z
      - .offset:         258
        .size:           2
        .value_kind:     hidden_remainder_x
      - .offset:         260
        .size:           2
        .value_kind:     hidden_remainder_y
      - .offset:         262
        .size:           2
        .value_kind:     hidden_remainder_z
      - .offset:         280
        .size:           8
        .value_kind:     hidden_global_offset_x
      - .offset:         288
        .size:           8
        .value_kind:     hidden_global_offset_y
      - .offset:         296
        .size:           8
        .value_kind:     hidden_global_offset_z
      - .offset:         304
        .size:           2
        .value_kind:     hidden_grid_dims
      - .offset:         328
        .size:           8
        .value_kind:     hidden_multigrid_sync_arg
      - .offset:         360
        .size:           4
        .value_kind:     hidden_dynamic_lds_size
    .group_segment_fixed_size: 0
    .kernarg_segment_align: 8
    .kernarg_segment_size: 496
    .language:       OpenCL C
    .language_version:
      - 2
      - 0
    .max_flat_workgroup_size: 512
    .name:           _Z4mega4Args
    .private_segment_fixed_size: 0
    .sgpr_count:     108
    .sgpr_spill_count: 93
    .symbol:         _Z4mega4Args.kd
    .uniform_work_group_size: 1
    .uses_dynamic_stack: false
    .vgpr_count:     238
    .vgpr_spill_count: 0
    .wavefront_size: 64
